# issue the six LDS-DMA loads of each SP2 load segment before its eight ds_reads (all four GEMM loops)
# baseline (speedup 1.0000x reference)
; #define PG8_STAGE(bufoff, gbase, voff) do { _Pragma("unroll") for (int _i = 0; _i < 2; ++_i) \
;         __builtin_amdgcn_global_load_lds((const unsigned*)((const char*)(gbase) + (voff)[_i]), (PG8_LAS unsigned*)(lds + (bufoff) + ldsw + _i * 8192), 16, 0, 0); } while (0)
; #define PG8_LDA(dst, b, h) do { _Pragma("unroll") for (int m = 0; m < 4; ++m) _Pragma("unroll") for (int k = 0; k < 2; ++k) dst[m][k] = *(const PG8_LAS bf16x8*)(lds + PG8_SA(b, h) + aoff + m * 2048 + k * 1024); } while (0)
; #define PG8_LDB(dst, b, h) do { _Pragma("unroll") for (int n = 0; n < 2; ++n) _Pragma("unroll") for (int k = 0; k < 2; ++k) dst[n][k] = *(const PG8_LAS bf16x8*)(lds + PG8_SB(b, h) + boff + n * 2048 + k * 1024); } while (0)
; #define PG8_MMA(ai, bj, At, Bt) do { __builtin_amdgcn_s_setprio(1); _Pragma("unroll") for (int m = 0; m < 4; ++m) _Pragma("unroll") for (int n = 0; n < 2; ++n) _Pragma("unroll") for (int k = 0; k < 2; ++k) \
;         acc[ai][bj][m][n] = __builtin_amdgcn_mfma_f32_16x16x32_bf16(Bt[n][k], At[m][k], acc[ai][bj][m][n], 0, 0, 0); __builtin_amdgcn_s_setprio(0); } while (0)
; #define PG8_WAIT_V(n) asm volatile("s_waitcnt vmcnt(" #n ")" ::: "memory")
; #define PG8_WAIT_L(n) asm volatile("s_waitcnt lgkmcnt(" #n ")" ::: "memory")
; #define PG8_BAR __builtin_amdgcn_s_barrier()
; #define PG8_SCHED __builtin_amdgcn_sched_barrier(0)
; template <class Epi, class Sched, bool ALIGN_EPI = false, bool SP2 = false>
; __device__ __forceinline__ void gemm_phase(PG8_LAS unsigned char* lds, const Gemm g, const Sched& S, const Epi& E) {
;     ...
;             PG8_LDB(B0, 0, 0); PG8_LDB(B1, 0, 1); PG8_SCHED; PG8_LDA(At, 0, 0); PG8_STAGE(PG8_SA(1, 1), a1 + hstep, voffA);
;             PG8_WAIT_V(8); PG8_WAIT_L(0); PG8_BAR; PG8_MMA(0, 0, At, B0); PG8_MMA(0, 1, At, B1); PG8_BAR; PG8_SCHED;
;             PG8_LDA(At, 0, 1); PG8_STAGE(PG8_SB(0, 0), b2, voffB); PG8_STAGE(PG8_SB(0, 1), b2 + hstep, voffB); PG8_STAGE(PG8_SA(0, 0), a2, voffA);
.LBB0_110:
	s_add_u32 s46, s44, 0xfffc0080
	s_addc_u32 s47, s45, -1
	s_add_i32 s67, 0, 0x10000
	s_cmp_eq_u32 s66, 12
	s_cselect_b32 s49, s17, s47
	s_cselect_b32 s48, s62, s46
	v_add_u32_e32 v145, s67, v143
	s_cselect_b32 s47, s15, s65
	s_cselect_b32 s46, s63, s64
	s_add_i32 s70, 0, 0x14000
	ds_read_b128 v[146:149], v145
	ds_read_b128 v[150:153], v145 offset:1024
	ds_read_b128 v[154:157], v145 offset:2048
	ds_read_b128 v[158:161], v145 offset:3072
	v_add_u32_e32 v145, s70, v143
	ds_read_b128 v[176:179], v145
	ds_read_b128 v[180:183], v145 offset:1024
	ds_read_b128 v[184:187], v145 offset:2048
	ds_read_b128 v[188:191], v145 offset:3072
	v_lshl_add_u64 v[200:201], s[44:45], 0, v[138:139]
	s_add_i32 m0, s50, 0xc000
	ds_read_b128 v[192:195], v144
	ds_read_b128 v[196:199], v144 offset:1024
	ds_read_b128 v[208:211], v144 offset:2048
	ds_read_b128 v[212:215], v144 offset:3072
	ds_read_b128 v[216:219], v144 offset:4096
	ds_read_b128 v[220:223], v144 offset:5120
	ds_read_b128 v[224:227], v144 offset:6144
	ds_read_b128 v[228:231], v144 offset:7168
	global_load_lds_dwordx4 v[200:201], off
	v_lshl_add_u64 v[200:201], s[44:45], 0, v[140:141]
	s_add_i32 m0, s50, 0xe000
	s_nop 0
	global_load_lds_dwordx4 v[200:201], off
	s_waitcnt vmcnt(8)
	s_waitcnt lgkmcnt(0)
	s_barrier
	s_setprio 1
	s_waitcnt lgkmcnt(0)
	v_mfma_f32_16x16x32_bf16 v[126:129], v[146:149], v[192:195], v[126:129]
	v_mfma_f32_16x16x32_bf16 v[118:121], v[154:157], v[192:195], v[118:121]
	v_mfma_f32_16x16x32_bf16 v[110:113], v[146:149], v[208:211], v[110:113]
	v_mfma_f32_16x16x32_bf16 v[102:105], v[154:157], v[208:211], v[102:105]
	v_mfma_f32_16x16x32_bf16 v[94:97], v[146:149], v[216:219], v[94:97]
	v_mfma_f32_16x16x32_bf16 v[86:89], v[154:157], v[216:219], v[86:89]
	v_mfma_f32_16x16x32_bf16 v[76:79], v[146:149], v[224:227], v[76:79]
	v_mfma_f32_16x16x32_bf16 v[68:71], v[154:157], v[224:227], v[68:71]
	v_mfma_f32_16x16x32_bf16 v[126:129], v[150:153], v[196:199], v[126:129]
	v_mfma_f32_16x16x32_bf16 v[118:121], v[158:161], v[196:199], v[118:121]
	v_mfma_f32_16x16x32_bf16 v[110:113], v[150:153], v[212:215], v[110:113]
	v_mfma_f32_16x16x32_bf16 v[102:105], v[158:161], v[212:215], v[102:105]
	v_mfma_f32_16x16x32_bf16 v[94:97], v[150:153], v[220:223], v[94:97]
	v_mfma_f32_16x16x32_bf16 v[86:89], v[158:161], v[220:223], v[86:89]
	v_mfma_f32_16x16x32_bf16 v[76:79], v[150:153], v[228:231], v[76:79]
	v_mfma_f32_16x16x32_bf16 v[68:71], v[158:161], v[228:231], v[68:71]
	s_setprio 0
	s_setprio 1
	v_mfma_f32_16x16x32_bf16 v[122:125], v[176:179], v[192:195], v[122:125]
	v_mfma_f32_16x16x32_bf16 v[114:117], v[184:187], v[192:195], v[114:117]
	v_mfma_f32_16x16x32_bf16 v[106:109], v[176:179], v[208:211], v[106:109]
	v_mfma_f32_16x16x32_bf16 v[98:101], v[184:187], v[208:211], v[98:101]
	v_mfma_f32_16x16x32_bf16 v[90:93], v[176:179], v[216:219], v[90:93]
	v_mfma_f32_16x16x32_bf16 v[82:85], v[184:187], v[216:219], v[82:85]
	v_mfma_f32_16x16x32_bf16 v[72:75], v[176:179], v[224:227], v[72:75]
	v_mfma_f32_16x16x32_bf16 v[64:67], v[184:187], v[224:227], v[64:67]
	v_mfma_f32_16x16x32_bf16 v[122:125], v[180:183], v[196:199], v[122:125]
	v_mfma_f32_16x16x32_bf16 v[114:117], v[188:191], v[196:199], v[114:117]
	v_mfma_f32_16x16x32_bf16 v[106:109], v[180:183], v[212:215], v[106:109]
	v_mfma_f32_16x16x32_bf16 v[98:101], v[188:191], v[212:215], v[98:101]
	v_mfma_f32_16x16x32_bf16 v[90:93], v[180:183], v[220:223], v[90:93]
	v_mfma_f32_16x16x32_bf16 v[82:85], v[188:191], v[220:223], v[82:85]
	v_mfma_f32_16x16x32_bf16 v[72:75], v[180:183], v[228:231], v[72:75]
	v_mfma_f32_16x16x32_bf16 v[64:67], v[188:191], v[228:231], v[64:67]
	s_setprio 0
	s_barrier
	s_add_i32 s67, s67, s39
	v_lshl_add_u64 v[200:201], s[46:47], 0, v[134:135]
	s_mov_b32 m0, s67
	s_nop 0
	global_load_lds_dwordx4 v[200:201], off
	s_add_i32 m0, s67, 0x2000
	s_add_u32 s68, s46, 0x40000
	v_lshl_add_u64 v[232:233], s[46:47], 0, v[130:131]
	s_addc_u32 s69, s47, 0
	s_add_i32 s67, s70, s39
	global_load_lds_dwordx4 v[232:233], off
	v_lshl_add_u64 v[234:235], s[68:69], 0, v[134:135]
	s_mov_b32 m0, s67
	v_lshl_add_u64 v[236:237], s[48:49], 0, v[132:133]
	global_load_lds_dwordx4 v[234:235], off
	v_lshl_add_u64 v[234:235], s[68:69], 0, v[130:131]
	s_add_i32 m0, s67, 0x2000
	s_nop 0
	global_load_lds_dwordx4 v[234:235], off
	v_lshl_add_u64 v[234:235], s[48:49], 0, v[136:137]
	s_mov_b32 m0, s50
	s_nop 0
	global_load_lds_dwordx4 v[234:235], off
	s_mov_b32 m0, s51
	s_nop 0
	global_load_lds_dwordx4 v[236:237], off
	ds_read_b128 v[192:195], v144 offset:16384
	ds_read_b128 v[196:199], v144 offset:17408
	ds_read_b128 v[208:211], v144 offset:18432
	ds_read_b128 v[212:215], v144 offset:19456
	ds_read_b128 v[216:219], v144 offset:20480
	ds_read_b128 v[220:223], v144 offset:21504
	ds_read_b128 v[224:227], v144 offset:22528
	ds_read_b128 v[228:231], v144 offset:23552
	s_waitcnt vmcnt(8)
	s_waitcnt lgkmcnt(0)
	s_barrier
; #define PG8_STAGE(bufoff, gbase, voff) do { _Pragma("unroll") for (int _i = 0; _i < 2; ++_i) \
;         __builtin_amdgcn_global_load_lds((const unsigned*)((const char*)(gbase) + (voff)[_i]), (PG8_LAS unsigned*)(lds + (bufoff) + ldsw + _i * 8192), 16, 0, 0); } while (0)
; #define PG8_LDA(dst, b, h) do { _Pragma("unroll") for (int m = 0; m < 4; ++m) _Pragma("unroll") for (int k = 0; k < 2; ++k) dst[m][k] = *(const PG8_LAS bf16x8*)(lds + PG8_SA(b, h) + aoff + m * 2048 + k * 1024); } while (0)
; #define PG8_LDB(dst, b, h) do { _Pragma("unroll") for (int n = 0; n < 2; ++n) _Pragma("unroll") for (int k = 0; k < 2; ++k) dst[n][k] = *(const PG8_LAS bf16x8*)(lds + PG8_SB(b, h) + boff + n * 2048 + k * 1024); } while (0)
; #define PG8_MMA(ai, bj, At, Bt) do { __builtin_amdgcn_s_setprio(1); _Pragma("unroll") for (int m = 0; m < 4; ++m) _Pragma("unroll") for (int n = 0; n < 2; ++n) _Pragma("unroll") for (int k = 0; k < 2; ++k) \
;         acc[ai][bj][m][n] = __builtin_amdgcn_mfma_f32_16x16x32_bf16(Bt[n][k], At[m][k], acc[ai][bj][m][n], 0, 0, 0); __builtin_amdgcn_s_setprio(0); } while (0)
; #define PG8_WAIT_V(n) asm volatile("s_waitcnt vmcnt(" #n ")" ::: "memory")
; #define PG8_WAIT_L(n) asm volatile("s_waitcnt lgkmcnt(" #n ")" ::: "memory")
; #define PG8_BAR __builtin_amdgcn_s_barrier()
; #define PG8_SCHED __builtin_amdgcn_sched_barrier(0)
; template <class Epi, class Sched, bool ALIGN_EPI = false, bool SP2 = false>
; __device__ __forceinline__ void gemm_phase(PG8_LAS unsigned char* lds, const Gemm g, const Sched& S, const Epi& E) {
;     ...
;             PG8_WAIT_V(8); PG8_WAIT_L(0); PG8_BAR; PG8_MMA(1, 0, At, B0); PG8_MMA(1, 1, At, B1); PG8_BAR; PG8_SCHED;
;             PG8_LDB(B0, 1, 0); PG8_LDB(B1, 1, 1); PG8_SCHED; PG8_LDA(At, 1, 0); PG8_STAGE(PG8_SA(0, 1), a2 + hstep, voffA);
;             PG8_WAIT_V(8); PG8_WAIT_L(0); PG8_BAR; PG8_MMA(0, 0, At, B0); PG8_MMA(0, 1, At, B1); PG8_BAR; PG8_SCHED;
	s_setprio 1
	s_waitcnt lgkmcnt(0)
	v_mfma_f32_16x16x32_bf16 v[60:63], v[146:149], v[192:195], v[60:63]
	v_mfma_f32_16x16x32_bf16 v[52:55], v[154:157], v[192:195], v[52:55]
	v_mfma_f32_16x16x32_bf16 v[44:47], v[146:149], v[208:211], v[44:47]
	v_mfma_f32_16x16x32_bf16 v[36:39], v[154:157], v[208:211], v[36:39]
	v_mfma_f32_16x16x32_bf16 v[28:31], v[146:149], v[216:219], v[28:31]
	v_mfma_f32_16x16x32_bf16 v[20:23], v[154:157], v[216:219], v[20:23]
	v_mfma_f32_16x16x32_bf16 v[12:15], v[146:149], v[224:227], v[12:15]
	v_mfma_f32_16x16x32_bf16 v[4:7], v[154:157], v[224:227], v[4:7]
	v_mfma_f32_16x16x32_bf16 v[60:63], v[150:153], v[196:199], v[60:63]
	v_mfma_f32_16x16x32_bf16 v[52:55], v[158:161], v[196:199], v[52:55]
	v_mfma_f32_16x16x32_bf16 v[44:47], v[150:153], v[212:215], v[44:47]
	v_mfma_f32_16x16x32_bf16 v[36:39], v[158:161], v[212:215], v[36:39]
	v_mfma_f32_16x16x32_bf16 v[28:31], v[150:153], v[220:223], v[28:31]
	v_mfma_f32_16x16x32_bf16 v[20:23], v[158:161], v[220:223], v[20:23]
	v_mfma_f32_16x16x32_bf16 v[12:15], v[150:153], v[228:231], v[12:15]
	v_mfma_f32_16x16x32_bf16 v[4:7], v[158:161], v[228:231], v[4:7]
	s_setprio 0
	s_setprio 1
	v_mfma_f32_16x16x32_bf16 v[56:59], v[176:179], v[192:195], v[56:59]
	v_mfma_f32_16x16x32_bf16 v[48:51], v[184:187], v[192:195], v[48:51]
	v_mfma_f32_16x16x32_bf16 v[40:43], v[176:179], v[208:211], v[40:43]
	v_mfma_f32_16x16x32_bf16 v[32:35], v[184:187], v[208:211], v[32:35]
	v_mfma_f32_16x16x32_bf16 v[24:27], v[176:179], v[216:219], v[24:27]
	v_mfma_f32_16x16x32_bf16 v[16:19], v[184:187], v[216:219], v[16:19]
	v_mfma_f32_16x16x32_bf16 v[8:11], v[176:179], v[224:227], v[8:11]
	v_mfma_f32_16x16x32_bf16 v[0:3], v[184:187], v[224:227], v[0:3]
	v_mfma_f32_16x16x32_bf16 v[56:59], v[180:183], v[196:199], v[56:59]
	v_mfma_f32_16x16x32_bf16 v[48:51], v[188:191], v[196:199], v[48:51]
	v_mfma_f32_16x16x32_bf16 v[40:43], v[180:183], v[212:215], v[40:43]
	v_mfma_f32_16x16x32_bf16 v[32:35], v[188:191], v[212:215], v[32:35]
	v_mfma_f32_16x16x32_bf16 v[24:27], v[180:183], v[220:223], v[24:27]
	v_mfma_f32_16x16x32_bf16 v[16:19], v[188:191], v[220:223], v[16:19]
	v_mfma_f32_16x16x32_bf16 v[8:11], v[180:183], v[228:231], v[8:11]
	v_mfma_f32_16x16x32_bf16 v[0:3], v[188:191], v[228:231], v[0:3]
	s_setprio 0
	s_barrier
	s_add_i32 s67, 0, 0x18000
	v_add_u32_e32 v145, s67, v143
	s_add_i32 s68, 0, 0x1c000
	ds_read_b128 v[146:149], v145
	ds_read_b128 v[150:153], v145 offset:1024
	ds_read_b128 v[154:157], v145 offset:2048
	ds_read_b128 v[158:161], v145 offset:3072
	v_add_u32_e32 v145, s68, v143
	ds_read_b128 v[176:179], v145
	ds_read_b128 v[180:183], v145 offset:1024
	ds_read_b128 v[184:187], v145 offset:2048
	ds_read_b128 v[188:191], v145 offset:3072
	s_add_u32 s48, s48, 0x40000
	s_addc_u32 s49, s49, 0
	s_mov_b32 m0, s52
	v_lshl_add_u64 v[238:239], s[48:49], 0, v[136:137]
	ds_read_b128 v[192:195], v144 offset:32768
	ds_read_b128 v[196:199], v144 offset:33792
	ds_read_b128 v[208:211], v144 offset:34816
	ds_read_b128 v[212:215], v144 offset:35840
	ds_read_b128 v[216:219], v144 offset:36864
	ds_read_b128 v[220:223], v144 offset:37888
	ds_read_b128 v[224:227], v144 offset:38912
	ds_read_b128 v[228:231], v144 offset:39936
	global_load_lds_dwordx4 v[238:239], off
	v_lshl_add_u64 v[238:239], s[48:49], 0, v[132:133]
	s_mov_b32 m0, s53
	s_nop 0
	global_load_lds_dwordx4 v[238:239], off
	s_waitcnt vmcnt(8)
	s_waitcnt lgkmcnt(0)
	s_barrier
	s_setprio 1
	s_waitcnt lgkmcnt(0)
	v_mfma_f32_16x16x32_bf16 v[126:129], v[146:149], v[192:195], v[126:129]
	v_mfma_f32_16x16x32_bf16 v[118:121], v[154:157], v[192:195], v[118:121]
	v_mfma_f32_16x16x32_bf16 v[110:113], v[146:149], v[208:211], v[110:113]
	v_mfma_f32_16x16x32_bf16 v[102:105], v[154:157], v[208:211], v[102:105]
	v_mfma_f32_16x16x32_bf16 v[94:97], v[146:149], v[216:219], v[94:97]
	v_mfma_f32_16x16x32_bf16 v[86:89], v[154:157], v[216:219], v[86:89]
	v_mfma_f32_16x16x32_bf16 v[76:79], v[146:149], v[224:227], v[76:79]
	v_mfma_f32_16x16x32_bf16 v[68:71], v[154:157], v[224:227], v[68:71]
	v_mfma_f32_16x16x32_bf16 v[126:129], v[150:153], v[196:199], v[126:129]
	v_mfma_f32_16x16x32_bf16 v[118:121], v[158:161], v[196:199], v[118:121]
	v_mfma_f32_16x16x32_bf16 v[110:113], v[150:153], v[212:215], v[110:113]
	v_mfma_f32_16x16x32_bf16 v[102:105], v[158:161], v[212:215], v[102:105]
	v_mfma_f32_16x16x32_bf16 v[94:97], v[150:153], v[220:223], v[94:97]
	v_mfma_f32_16x16x32_bf16 v[86:89], v[158:161], v[220:223], v[86:89]
	v_mfma_f32_16x16x32_bf16 v[76:79], v[150:153], v[228:231], v[76:79]
	v_mfma_f32_16x16x32_bf16 v[68:71], v[158:161], v[228:231], v[68:71]
	s_setprio 0
	s_setprio 1
	v_mfma_f32_16x16x32_bf16 v[122:125], v[176:179], v[192:195], v[122:125]
	v_mfma_f32_16x16x32_bf16 v[114:117], v[184:187], v[192:195], v[114:117]
	v_mfma_f32_16x16x32_bf16 v[106:109], v[176:179], v[208:211], v[106:109]
	v_mfma_f32_16x16x32_bf16 v[98:101], v[184:187], v[208:211], v[98:101]
	v_mfma_f32_16x16x32_bf16 v[90:93], v[176:179], v[216:219], v[90:93]
	v_mfma_f32_16x16x32_bf16 v[82:85], v[184:187], v[216:219], v[82:85]
	v_mfma_f32_16x16x32_bf16 v[72:75], v[176:179], v[224:227], v[72:75]
	v_mfma_f32_16x16x32_bf16 v[64:67], v[184:187], v[224:227], v[64:67]
	v_mfma_f32_16x16x32_bf16 v[122:125], v[180:183], v[196:199], v[122:125]
	v_mfma_f32_16x16x32_bf16 v[114:117], v[188:191], v[196:199], v[114:117]
	v_mfma_f32_16x16x32_bf16 v[106:109], v[180:183], v[212:215], v[106:109]
	v_mfma_f32_16x16x32_bf16 v[98:101], v[188:191], v[212:215], v[98:101]
	v_mfma_f32_16x16x32_bf16 v[90:93], v[180:183], v[220:223], v[90:93]
	v_mfma_f32_16x16x32_bf16 v[82:85], v[188:191], v[220:223], v[82:85]
	v_mfma_f32_16x16x32_bf16 v[72:75], v[180:183], v[228:231], v[72:75]
	v_mfma_f32_16x16x32_bf16 v[64:67], v[188:191], v[228:231], v[64:67]
	s_setprio 0
	s_barrier
; #define PG8_STAGE(bufoff, gbase, voff) do { _Pragma("unroll") for (int _i = 0; _i < 2; ++_i) \
;         __builtin_amdgcn_global_load_lds((const unsigned*)((const char*)(gbase) + (voff)[_i]), (PG8_LAS unsigned*)(lds + (bufoff) + ldsw + _i * 8192), 16, 0, 0); } while (0)
; #define PG8_LDA(dst, b, h) do { _Pragma("unroll") for (int m = 0; m < 4; ++m) _Pragma("unroll") for (int k = 0; k < 2; ++k) dst[m][k] = *(const PG8_LAS bf16x8*)(lds + PG8_SA(b, h) + aoff + m * 2048 + k * 1024); } while (0)
; #define PG8_MMA(ai, bj, At, Bt) do { __builtin_amdgcn_s_setprio(1); _Pragma("unroll") for (int m = 0; m < 4; ++m) _Pragma("unroll") for (int n = 0; n < 2; ++n) _Pragma("unroll") for (int k = 0; k < 2; ++k) \
;         acc[ai][bj][m][n] = __builtin_amdgcn_mfma_f32_16x16x32_bf16(Bt[n][k], At[m][k], acc[ai][bj][m][n], 0, 0, 0); __builtin_amdgcn_s_setprio(0); } while (0)
; #define PG8_WAIT_V(n) asm volatile("s_waitcnt vmcnt(" #n ")" ::: "memory")
; #define PG8_WAIT_L(n) asm volatile("s_waitcnt lgkmcnt(" #n ")" ::: "memory")
; #define PG8_BAR __builtin_amdgcn_s_barrier()
; #define PG8_SCHED __builtin_amdgcn_sched_barrier(0)
; template <class Epi, class Sched, bool ALIGN_EPI = false, bool SP2 = false>
; __device__ __forceinline__ void gemm_phase(PG8_LAS unsigned char* lds, const Gemm g, const Sched& S, const Epi& E) {
;     ...
;         for (int t = 0; t < nt; t += 2) {
;             if constexpr (Epi::PF_TRIPS > 0) { if (t == nt - 2 * Epi::PF_TRIPS) E.prefetch(cur, tid, lds + STAGE_BYTES + wid * 512); }
;             const bool last = (t == nt - 2);
;             const char* a1 = cA + (size_t)(t + 1) * kstep;
;             const char* a2 = last ? nA : cA + (size_t)(t + 2) * kstep; const char* b2 = last ? nB : cB + (size_t)(t + 2) * kstep;
;             const char* a3 = a2 + kstep; const char* b3 = b2 + kstep;
;     ...
;             PG8_LDA(At, 1, 1); PG8_STAGE(PG8_SB(1, 0), b3, voffB); PG8_STAGE(PG8_SB(1, 1), b3 + hstep, voffB); PG8_STAGE(PG8_SA(1, 0), a3, voffA);
;             PG8_WAIT_V(8); PG8_WAIT_L(0); PG8_BAR; PG8_MMA(1, 0, At, B0); PG8_MMA(1, 1, At, B1); PG8_BAR; PG8_SCHED;
	s_add_i32 s48, s67, s39
	v_lshl_add_u64 v[200:201], v[200:201], 0, s[40:41]
	s_mov_b32 m0, s48
	s_nop 0
	global_load_lds_dwordx4 v[200:201], off
	s_add_i32 m0, s48, 0x2000
	s_add_u32 s46, s46, 0x40080
	v_lshl_add_u64 v[200:201], v[232:233], 0, s[40:41]
	s_addc_u32 s47, s47, 0
	s_add_i32 s48, s68, s39
	global_load_lds_dwordx4 v[200:201], off
	v_lshl_add_u64 v[200:201], s[46:47], 0, v[134:135]
	s_mov_b32 m0, s48
	s_nop 0
	global_load_lds_dwordx4 v[200:201], off
	v_lshl_add_u64 v[200:201], s[46:47], 0, v[130:131]
	s_add_i32 m0, s48, 0x2000
	s_nop 0
	global_load_lds_dwordx4 v[200:201], off
	v_lshl_add_u64 v[200:201], v[234:235], 0, s[40:41]
	s_mov_b32 m0, s56
	s_nop 0
	global_load_lds_dwordx4 v[200:201], off
	v_lshl_add_u64 v[200:201], v[236:237], 0, s[40:41]
	s_mov_b32 m0, s57
	s_nop 0
	global_load_lds_dwordx4 v[200:201], off
	ds_read_b128 v[192:195], v144 offset:49152
	ds_read_b128 v[196:199], v144 offset:50176
	ds_read_b128 v[208:211], v144 offset:51200
	ds_read_b128 v[212:215], v144 offset:52224
	ds_read_b128 v[216:219], v144 offset:53248
	ds_read_b128 v[220:223], v144 offset:54272
	ds_read_b128 v[224:227], v144 offset:55296
	ds_read_b128 v[228:231], v144 offset:56320
	s_waitcnt vmcnt(8)
	s_waitcnt lgkmcnt(0)
	s_barrier
	s_setprio 1
	s_waitcnt lgkmcnt(0)
	v_mfma_f32_16x16x32_bf16 v[60:63], v[146:149], v[192:195], v[60:63]
	v_mfma_f32_16x16x32_bf16 v[52:55], v[154:157], v[192:195], v[52:55]
	v_mfma_f32_16x16x32_bf16 v[44:47], v[146:149], v[208:211], v[44:47]
	v_mfma_f32_16x16x32_bf16 v[36:39], v[154:157], v[208:211], v[36:39]
	v_mfma_f32_16x16x32_bf16 v[28:31], v[146:149], v[216:219], v[28:31]
	v_mfma_f32_16x16x32_bf16 v[20:23], v[154:157], v[216:219], v[20:23]
	v_mfma_f32_16x16x32_bf16 v[12:15], v[146:149], v[224:227], v[12:15]
	v_mfma_f32_16x16x32_bf16 v[4:7], v[154:157], v[224:227], v[4:7]
	v_mfma_f32_16x16x32_bf16 v[60:63], v[150:153], v[196:199], v[60:63]
	v_mfma_f32_16x16x32_bf16 v[52:55], v[158:161], v[196:199], v[52:55]
	v_mfma_f32_16x16x32_bf16 v[44:47], v[150:153], v[212:215], v[44:47]
	v_mfma_f32_16x16x32_bf16 v[36:39], v[158:161], v[212:215], v[36:39]
	v_mfma_f32_16x16x32_bf16 v[28:31], v[150:153], v[220:223], v[28:31]
	v_mfma_f32_16x16x32_bf16 v[20:23], v[158:161], v[220:223], v[20:23]
	v_mfma_f32_16x16x32_bf16 v[12:15], v[150:153], v[228:231], v[12:15]
	v_mfma_f32_16x16x32_bf16 v[4:7], v[158:161], v[228:231], v[4:7]
	s_setprio 0
	s_setprio 1
	v_mfma_f32_16x16x32_bf16 v[56:59], v[176:179], v[192:195], v[56:59]
	v_mfma_f32_16x16x32_bf16 v[48:51], v[184:187], v[192:195], v[48:51]
	v_mfma_f32_16x16x32_bf16 v[40:43], v[176:179], v[208:211], v[40:43]
	v_mfma_f32_16x16x32_bf16 v[32:35], v[184:187], v[208:211], v[32:35]
	v_mfma_f32_16x16x32_bf16 v[24:27], v[176:179], v[216:219], v[24:27]
	v_mfma_f32_16x16x32_bf16 v[16:19], v[184:187], v[216:219], v[16:19]
	v_mfma_f32_16x16x32_bf16 v[8:11], v[176:179], v[224:227], v[8:11]
	v_mfma_f32_16x16x32_bf16 v[0:3], v[184:187], v[224:227], v[0:3]
	v_mfma_f32_16x16x32_bf16 v[56:59], v[180:183], v[196:199], v[56:59]
	v_mfma_f32_16x16x32_bf16 v[48:51], v[188:191], v[196:199], v[48:51]
	v_mfma_f32_16x16x32_bf16 v[40:43], v[180:183], v[212:215], v[40:43]
	v_mfma_f32_16x16x32_bf16 v[32:35], v[188:191], v[212:215], v[32:35]
	v_mfma_f32_16x16x32_bf16 v[24:27], v[180:183], v[220:223], v[24:27]
	v_mfma_f32_16x16x32_bf16 v[16:19], v[188:191], v[220:223], v[16:19]
	v_mfma_f32_16x16x32_bf16 v[8:11], v[180:183], v[228:231], v[8:11]
	v_mfma_f32_16x16x32_bf16 v[0:3], v[188:191], v[228:231], v[0:3]
	s_setprio 0
	s_barrier
	s_add_i32 s66, s66, 2
	s_add_u32 s44, s44, 0x100
	s_addc_u32 s45, s45, 0
	s_add_u32 s64, s64, 0x100
	s_addc_u32 s65, s65, 0
	s_cmp_gt_u32 s66, 13
	s_cbranch_scc0 .LBB0_110
	s_and_b64 vcc, exec, s[12:13]
	s_cbranch_vccz .LBB0_113
	s_barrier

; #define PG8_STAGE(bufoff, gbase, voff) do { _Pragma("unroll") for (int _i = 0; _i < 2; ++_i) \
;         __builtin_amdgcn_global_load_lds((const unsigned*)((const char*)(gbase) + (voff)[_i]), (PG8_LAS unsigned*)(lds + (bufoff) + ldsw + _i * 8192), 16, 0, 0); } while (0)
; #define PG8_LDA(dst, b, h) do { _Pragma("unroll") for (int m = 0; m < 4; ++m) _Pragma("unroll") for (int k = 0; k < 2; ++k) dst[m][k] = *(const PG8_LAS bf16x8*)(lds + PG8_SA(b, h) + aoff + m * 2048 + k * 1024); } while (0)
; #define PG8_LDB(dst, b, h) do { _Pragma("unroll") for (int n = 0; n < 2; ++n) _Pragma("unroll") for (int k = 0; k < 2; ++k) dst[n][k] = *(const PG8_LAS bf16x8*)(lds + PG8_SB(b, h) + boff + n * 2048 + k * 1024); } while (0)
; #define PG8_MMA(ai, bj, At, Bt) do { __builtin_amdgcn_s_setprio(1); _Pragma("unroll") for (int m = 0; m < 4; ++m) _Pragma("unroll") for (int n = 0; n < 2; ++n) _Pragma("unroll") for (int k = 0; k < 2; ++k) \
;         acc[ai][bj][m][n] = __builtin_amdgcn_mfma_f32_16x16x32_bf16(Bt[n][k], At[m][k], acc[ai][bj][m][n], 0, 0, 0); __builtin_amdgcn_s_setprio(0); } while (0)
; #define PG8_WAIT_V(n) asm volatile("s_waitcnt vmcnt(" #n ")" ::: "memory")
; #define PG8_WAIT_L(n) asm volatile("s_waitcnt lgkmcnt(" #n ")" ::: "memory")
; #define PG8_BAR __builtin_amdgcn_s_barrier()
; #define PG8_SCHED __builtin_amdgcn_sched_barrier(0)
; template <class Epi, class Sched, bool ALIGN_EPI = false, bool SP2 = false>
; __device__ __forceinline__ void gemm_phase(PG8_LAS unsigned char* lds, const Gemm g, const Sched& S, const Epi& E) {
;     ...
;             PG8_LDB(B0, 0, 0); PG8_LDB(B1, 0, 1); PG8_SCHED; PG8_LDA(At, 0, 0); PG8_STAGE(PG8_SA(1, 1), a1 + hstep, voffA);
;             PG8_WAIT_V(8); PG8_WAIT_L(0); PG8_BAR; PG8_MMA(0, 0, At, B0); PG8_MMA(0, 1, At, B1); PG8_BAR; PG8_SCHED;
;             PG8_LDA(At, 0, 1); PG8_STAGE(PG8_SB(0, 0), b2, voffB); PG8_STAGE(PG8_SB(0, 1), b2 + hstep, voffB); PG8_STAGE(PG8_SA(0, 0), a2, voffA);
.LBB0_129:
	s_add_u32 s48, s46, 0xfffc0080
	s_addc_u32 s49, s47, -1
	s_add_i32 s69, 0, 0x10000
	s_cmp_eq_u32 s68, 12
	s_cselect_b32 s51, s19, s49
	s_cselect_b32 s50, s64, s48
	v_add_u32_e32 v142, s69, v148
	s_cselect_b32 s49, s17, s67
	s_cselect_b32 s48, s65, s66
	s_add_i32 s72, 0, 0x14000
	ds_read_b128 v[150:153], v142
	ds_read_b128 v[154:157], v142 offset:1024
	ds_read_b128 v[158:161], v142 offset:2048
	ds_read_b128 v[176:179], v142 offset:3072
	v_add_u32_e32 v142, s72, v148
	ds_read_b128 v[180:183], v142
	ds_read_b128 v[184:187], v142 offset:1024
	ds_read_b128 v[188:191], v142 offset:2048
	ds_read_b128 v[192:195], v142 offset:3072
	v_lshl_add_u64 v[142:143], s[46:47], 0, v[138:139]
	s_add_i32 m0, s53, 0xc000
	ds_read_b128 v[196:199], v149
	ds_read_b128 v[208:211], v149 offset:1024
	ds_read_b128 v[212:215], v149 offset:2048
	ds_read_b128 v[216:219], v149 offset:3072
	ds_read_b128 v[220:223], v149 offset:4096
	ds_read_b128 v[224:227], v149 offset:5120
	ds_read_b128 v[228:231], v149 offset:6144
	ds_read_b128 v[232:235], v149 offset:7168
	global_load_lds_dwordx4 v[142:143], off
	v_lshl_add_u64 v[142:143], s[46:47], 0, v[140:141]
	s_add_i32 m0, s53, 0xe000
	s_nop 0
	global_load_lds_dwordx4 v[142:143], off
	s_waitcnt vmcnt(8)
	s_waitcnt lgkmcnt(0)
	s_barrier
	s_setprio 1
	s_waitcnt lgkmcnt(0)
	v_mfma_f32_16x16x32_bf16 v[126:129], v[150:153], v[196:199], v[126:129]
	v_mfma_f32_16x16x32_bf16 v[122:125], v[158:161], v[196:199], v[122:125]
	v_mfma_f32_16x16x32_bf16 v[114:117], v[150:153], v[212:215], v[114:117]
	v_mfma_f32_16x16x32_bf16 v[106:109], v[158:161], v[212:215], v[106:109]
	v_mfma_f32_16x16x32_bf16 v[98:101], v[150:153], v[220:223], v[98:101]
	v_mfma_f32_16x16x32_bf16 v[90:93], v[158:161], v[220:223], v[90:93]
	v_mfma_f32_16x16x32_bf16 v[82:85], v[150:153], v[228:231], v[82:85]
	v_mfma_f32_16x16x32_bf16 v[72:75], v[158:161], v[228:231], v[72:75]
	v_mfma_f32_16x16x32_bf16 v[126:129], v[154:157], v[208:211], v[126:129]
	v_mfma_f32_16x16x32_bf16 v[122:125], v[176:179], v[208:211], v[122:125]
	v_mfma_f32_16x16x32_bf16 v[114:117], v[154:157], v[216:219], v[114:117]
	v_mfma_f32_16x16x32_bf16 v[106:109], v[176:179], v[216:219], v[106:109]
	v_mfma_f32_16x16x32_bf16 v[98:101], v[154:157], v[224:227], v[98:101]
	v_mfma_f32_16x16x32_bf16 v[90:93], v[176:179], v[224:227], v[90:93]
	v_mfma_f32_16x16x32_bf16 v[82:85], v[154:157], v[232:235], v[82:85]
	v_mfma_f32_16x16x32_bf16 v[72:75], v[176:179], v[232:235], v[72:75]
	s_setprio 0
	s_setprio 1
	v_mfma_f32_16x16x32_bf16 v[118:121], v[180:183], v[196:199], v[118:121]
	v_mfma_f32_16x16x32_bf16 v[110:113], v[188:191], v[196:199], v[110:113]
	v_mfma_f32_16x16x32_bf16 v[102:105], v[180:183], v[212:215], v[102:105]
	v_mfma_f32_16x16x32_bf16 v[94:97], v[188:191], v[212:215], v[94:97]
	v_mfma_f32_16x16x32_bf16 v[86:89], v[180:183], v[220:223], v[86:89]
	v_mfma_f32_16x16x32_bf16 v[76:79], v[188:191], v[220:223], v[76:79]
	v_mfma_f32_16x16x32_bf16 v[68:71], v[180:183], v[228:231], v[68:71]
	v_mfma_f32_16x16x32_bf16 v[64:67], v[188:191], v[228:231], v[64:67]
	v_mfma_f32_16x16x32_bf16 v[118:121], v[184:187], v[208:211], v[118:121]
	v_mfma_f32_16x16x32_bf16 v[110:113], v[192:195], v[208:211], v[110:113]
	v_mfma_f32_16x16x32_bf16 v[102:105], v[184:187], v[216:219], v[102:105]
	v_mfma_f32_16x16x32_bf16 v[94:97], v[192:195], v[216:219], v[94:97]
	v_mfma_f32_16x16x32_bf16 v[86:89], v[184:187], v[224:227], v[86:89]
	v_mfma_f32_16x16x32_bf16 v[76:79], v[192:195], v[224:227], v[76:79]
	v_mfma_f32_16x16x32_bf16 v[68:71], v[184:187], v[232:235], v[68:71]
	v_mfma_f32_16x16x32_bf16 v[64:67], v[192:195], v[232:235], v[64:67]
	s_setprio 0
	s_barrier
	s_add_i32 s69, s69, s52
	v_lshl_add_u64 v[142:143], s[48:49], 0, v[134:135]
	s_mov_b32 m0, s69
	s_nop 0
	global_load_lds_dwordx4 v[142:143], off
	s_add_i32 m0, s69, 0x2000
	s_add_u32 s70, s48, 0x40000
	v_lshl_add_u64 v[146:147], s[48:49], 0, v[130:131]
	s_addc_u32 s71, s49, 0
	s_add_i32 s69, s72, s52
	global_load_lds_dwordx4 v[146:147], off
	v_lshl_add_u64 v[200:201], s[70:71], 0, v[134:135]
	s_mov_b32 m0, s69
	v_lshl_add_u64 v[236:237], s[50:51], 0, v[132:133]
	global_load_lds_dwordx4 v[200:201], off
	v_lshl_add_u64 v[200:201], s[70:71], 0, v[130:131]
	s_add_i32 m0, s69, 0x2000
	s_nop 0
	global_load_lds_dwordx4 v[200:201], off
	v_lshl_add_u64 v[200:201], s[50:51], 0, v[136:137]
	s_mov_b32 m0, s53
	s_nop 0
	global_load_lds_dwordx4 v[200:201], off
	s_mov_b32 m0, s54
	s_nop 0
	global_load_lds_dwordx4 v[236:237], off
	ds_read_b128 v[196:199], v149 offset:16384
	ds_read_b128 v[208:211], v149 offset:17408
	ds_read_b128 v[212:215], v149 offset:18432
	ds_read_b128 v[216:219], v149 offset:19456
	ds_read_b128 v[220:223], v149 offset:20480
	ds_read_b128 v[224:227], v149 offset:21504
	ds_read_b128 v[228:231], v149 offset:22528
	ds_read_b128 v[232:235], v149 offset:23552
	s_waitcnt vmcnt(8)
	s_waitcnt lgkmcnt(0)
	s_barrier
; #define PG8_STAGE(bufoff, gbase, voff) do { _Pragma("unroll") for (int _i = 0; _i < 2; ++_i) \
;         __builtin_amdgcn_global_load_lds((const unsigned*)((const char*)(gbase) + (voff)[_i]), (PG8_LAS unsigned*)(lds + (bufoff) + ldsw + _i * 8192), 16, 0, 0); } while (0)
; #define PG8_LDA(dst, b, h) do { _Pragma("unroll") for (int m = 0; m < 4; ++m) _Pragma("unroll") for (int k = 0; k < 2; ++k) dst[m][k] = *(const PG8_LAS bf16x8*)(lds + PG8_SA(b, h) + aoff + m * 2048 + k * 1024); } while (0)
; #define PG8_LDB(dst, b, h) do { _Pragma("unroll") for (int n = 0; n < 2; ++n) _Pragma("unroll") for (int k = 0; k < 2; ++k) dst[n][k] = *(const PG8_LAS bf16x8*)(lds + PG8_SB(b, h) + boff + n * 2048 + k * 1024); } while (0)
; #define PG8_MMA(ai, bj, At, Bt) do { __builtin_amdgcn_s_setprio(1); _Pragma("unroll") for (int m = 0; m < 4; ++m) _Pragma("unroll") for (int n = 0; n < 2; ++n) _Pragma("unroll") for (int k = 0; k < 2; ++k) \
;         acc[ai][bj][m][n] = __builtin_amdgcn_mfma_f32_16x16x32_bf16(Bt[n][k], At[m][k], acc[ai][bj][m][n], 0, 0, 0); __builtin_amdgcn_s_setprio(0); } while (0)
; #define PG8_WAIT_V(n) asm volatile("s_waitcnt vmcnt(" #n ")" ::: "memory")
; #define PG8_WAIT_L(n) asm volatile("s_waitcnt lgkmcnt(" #n ")" ::: "memory")
; #define PG8_BAR __builtin_amdgcn_s_barrier()
; #define PG8_SCHED __builtin_amdgcn_sched_barrier(0)
; template <class Epi, class Sched, bool ALIGN_EPI = false, bool SP2 = false>
; __device__ __forceinline__ void gemm_phase(PG8_LAS unsigned char* lds, const Gemm g, const Sched& S, const Epi& E) {
;     ...
;             PG8_WAIT_V(8); PG8_WAIT_L(0); PG8_BAR; PG8_MMA(1, 0, At, B0); PG8_MMA(1, 1, At, B1); PG8_BAR; PG8_SCHED;
;             PG8_LDB(B0, 1, 0); PG8_LDB(B1, 1, 1); PG8_SCHED; PG8_LDA(At, 1, 0); PG8_STAGE(PG8_SA(0, 1), a2 + hstep, voffA);
;             PG8_WAIT_V(8); PG8_WAIT_L(0); PG8_BAR; PG8_MMA(0, 0, At, B0); PG8_MMA(0, 1, At, B1); PG8_BAR; PG8_SCHED;
	s_setprio 1
	s_waitcnt lgkmcnt(0)
	v_mfma_f32_16x16x32_bf16 v[60:63], v[150:153], v[196:199], v[60:63]
	v_mfma_f32_16x16x32_bf16 v[56:59], v[158:161], v[196:199], v[56:59]
	v_mfma_f32_16x16x32_bf16 v[48:51], v[150:153], v[212:215], v[48:51]
	v_mfma_f32_16x16x32_bf16 v[40:43], v[158:161], v[212:215], v[40:43]
	v_mfma_f32_16x16x32_bf16 v[32:35], v[150:153], v[220:223], v[32:35]
	v_mfma_f32_16x16x32_bf16 v[24:27], v[158:161], v[220:223], v[24:27]
	v_mfma_f32_16x16x32_bf16 v[16:19], v[150:153], v[228:231], v[16:19]
	v_mfma_f32_16x16x32_bf16 v[8:11], v[158:161], v[228:231], v[8:11]
	v_mfma_f32_16x16x32_bf16 v[60:63], v[154:157], v[208:211], v[60:63]
	v_mfma_f32_16x16x32_bf16 v[56:59], v[176:179], v[208:211], v[56:59]
	v_mfma_f32_16x16x32_bf16 v[48:51], v[154:157], v[216:219], v[48:51]
	v_mfma_f32_16x16x32_bf16 v[40:43], v[176:179], v[216:219], v[40:43]
	v_mfma_f32_16x16x32_bf16 v[32:35], v[154:157], v[224:227], v[32:35]
	v_mfma_f32_16x16x32_bf16 v[24:27], v[176:179], v[224:227], v[24:27]
	v_mfma_f32_16x16x32_bf16 v[16:19], v[154:157], v[232:235], v[16:19]
	v_mfma_f32_16x16x32_bf16 v[8:11], v[176:179], v[232:235], v[8:11]
	s_setprio 0
	s_setprio 1
	v_mfma_f32_16x16x32_bf16 v[52:55], v[180:183], v[196:199], v[52:55]
	v_mfma_f32_16x16x32_bf16 v[44:47], v[188:191], v[196:199], v[44:47]
	v_mfma_f32_16x16x32_bf16 v[36:39], v[180:183], v[212:215], v[36:39]
	v_mfma_f32_16x16x32_bf16 v[28:31], v[188:191], v[212:215], v[28:31]
	v_mfma_f32_16x16x32_bf16 v[20:23], v[180:183], v[220:223], v[20:23]
	v_mfma_f32_16x16x32_bf16 v[12:15], v[188:191], v[220:223], v[12:15]
	v_mfma_f32_16x16x32_bf16 v[4:7], v[180:183], v[228:231], v[4:7]
	v_mfma_f32_16x16x32_bf16 v[0:3], v[188:191], v[228:231], v[0:3]
	v_mfma_f32_16x16x32_bf16 v[52:55], v[184:187], v[208:211], v[52:55]
	v_mfma_f32_16x16x32_bf16 v[44:47], v[192:195], v[208:211], v[44:47]
	v_mfma_f32_16x16x32_bf16 v[36:39], v[184:187], v[216:219], v[36:39]
	v_mfma_f32_16x16x32_bf16 v[28:31], v[192:195], v[216:219], v[28:31]
	v_mfma_f32_16x16x32_bf16 v[20:23], v[184:187], v[224:227], v[20:23]
	v_mfma_f32_16x16x32_bf16 v[12:15], v[192:195], v[224:227], v[12:15]
	v_mfma_f32_16x16x32_bf16 v[4:7], v[184:187], v[232:235], v[4:7]
	v_mfma_f32_16x16x32_bf16 v[0:3], v[192:195], v[232:235], v[0:3]
	s_setprio 0
	s_barrier
	s_add_i32 s69, 0, 0x18000
	v_add_u32_e32 v144, s69, v148
	s_add_i32 s70, 0, 0x1c000
	ds_read_b128 v[150:153], v144
	ds_read_b128 v[154:157], v144 offset:1024
	ds_read_b128 v[158:161], v144 offset:2048
	ds_read_b128 v[176:179], v144 offset:3072
	v_add_u32_e32 v144, s70, v148
	ds_read_b128 v[180:183], v144
	ds_read_b128 v[184:187], v144 offset:1024
	ds_read_b128 v[188:191], v144 offset:2048
	ds_read_b128 v[192:195], v144 offset:3072
	s_add_u32 s50, s50, 0x40000
	s_addc_u32 s51, s51, 0
	s_mov_b32 m0, s55
	v_lshl_add_u64 v[238:239], s[50:51], 0, v[136:137]
	ds_read_b128 v[196:199], v149 offset:32768
	ds_read_b128 v[208:211], v149 offset:33792
	ds_read_b128 v[212:215], v149 offset:34816
	ds_read_b128 v[216:219], v149 offset:35840
	ds_read_b128 v[220:223], v149 offset:36864
	ds_read_b128 v[224:227], v149 offset:37888
	ds_read_b128 v[228:231], v149 offset:38912
	ds_read_b128 v[232:235], v149 offset:39936
	global_load_lds_dwordx4 v[238:239], off
	v_lshl_add_u64 v[238:239], s[50:51], 0, v[132:133]
	s_mov_b32 m0, s56
	s_nop 0
	global_load_lds_dwordx4 v[238:239], off
	s_waitcnt vmcnt(8)
	s_waitcnt lgkmcnt(0)
	s_barrier
	s_setprio 1
	s_waitcnt lgkmcnt(0)
	v_mfma_f32_16x16x32_bf16 v[126:129], v[150:153], v[196:199], v[126:129]
	v_mfma_f32_16x16x32_bf16 v[122:125], v[158:161], v[196:199], v[122:125]
	v_mfma_f32_16x16x32_bf16 v[114:117], v[150:153], v[212:215], v[114:117]
	v_mfma_f32_16x16x32_bf16 v[106:109], v[158:161], v[212:215], v[106:109]
	v_mfma_f32_16x16x32_bf16 v[98:101], v[150:153], v[220:223], v[98:101]
	v_mfma_f32_16x16x32_bf16 v[90:93], v[158:161], v[220:223], v[90:93]
	v_mfma_f32_16x16x32_bf16 v[82:85], v[150:153], v[228:231], v[82:85]
	v_mfma_f32_16x16x32_bf16 v[72:75], v[158:161], v[228:231], v[72:75]
	v_mfma_f32_16x16x32_bf16 v[126:129], v[154:157], v[208:211], v[126:129]
	v_mfma_f32_16x16x32_bf16 v[122:125], v[176:179], v[208:211], v[122:125]
	v_mfma_f32_16x16x32_bf16 v[114:117], v[154:157], v[216:219], v[114:117]
	v_mfma_f32_16x16x32_bf16 v[106:109], v[176:179], v[216:219], v[106:109]
	v_mfma_f32_16x16x32_bf16 v[98:101], v[154:157], v[224:227], v[98:101]
	v_mfma_f32_16x16x32_bf16 v[90:93], v[176:179], v[224:227], v[90:93]
	v_mfma_f32_16x16x32_bf16 v[82:85], v[154:157], v[232:235], v[82:85]
	v_mfma_f32_16x16x32_bf16 v[72:75], v[176:179], v[232:235], v[72:75]
	s_setprio 0
	s_setprio 1
	v_mfma_f32_16x16x32_bf16 v[118:121], v[180:183], v[196:199], v[118:121]
	v_mfma_f32_16x16x32_bf16 v[110:113], v[188:191], v[196:199], v[110:113]
	v_mfma_f32_16x16x32_bf16 v[102:105], v[180:183], v[212:215], v[102:105]
	v_mfma_f32_16x16x32_bf16 v[94:97], v[188:191], v[212:215], v[94:97]
	v_mfma_f32_16x16x32_bf16 v[86:89], v[180:183], v[220:223], v[86:89]
	v_mfma_f32_16x16x32_bf16 v[76:79], v[188:191], v[220:223], v[76:79]
	v_mfma_f32_16x16x32_bf16 v[68:71], v[180:183], v[228:231], v[68:71]
	v_mfma_f32_16x16x32_bf16 v[64:67], v[188:191], v[228:231], v[64:67]
	v_mfma_f32_16x16x32_bf16 v[118:121], v[184:187], v[208:211], v[118:121]
	v_mfma_f32_16x16x32_bf16 v[110:113], v[192:195], v[208:211], v[110:113]
	v_mfma_f32_16x16x32_bf16 v[102:105], v[184:187], v[216:219], v[102:105]
	v_mfma_f32_16x16x32_bf16 v[94:97], v[192:195], v[216:219], v[94:97]
	v_mfma_f32_16x16x32_bf16 v[86:89], v[184:187], v[224:227], v[86:89]
	v_mfma_f32_16x16x32_bf16 v[76:79], v[192:195], v[224:227], v[76:79]
	v_mfma_f32_16x16x32_bf16 v[68:71], v[184:187], v[232:235], v[68:71]
	v_mfma_f32_16x16x32_bf16 v[64:67], v[192:195], v[232:235], v[64:67]
	s_setprio 0
	s_barrier
; #define PG8_STAGE(bufoff, gbase, voff) do { _Pragma("unroll") for (int _i = 0; _i < 2; ++_i) \
;         __builtin_amdgcn_global_load_lds((const unsigned*)((const char*)(gbase) + (voff)[_i]), (PG8_LAS unsigned*)(lds + (bufoff) + ldsw + _i * 8192), 16, 0, 0); } while (0)
; #define PG8_LDA(dst, b, h) do { _Pragma("unroll") for (int m = 0; m < 4; ++m) _Pragma("unroll") for (int k = 0; k < 2; ++k) dst[m][k] = *(const PG8_LAS bf16x8*)(lds + PG8_SA(b, h) + aoff + m * 2048 + k * 1024); } while (0)
; #define PG8_MMA(ai, bj, At, Bt) do { __builtin_amdgcn_s_setprio(1); _Pragma("unroll") for (int m = 0; m < 4; ++m) _Pragma("unroll") for (int n = 0; n < 2; ++n) _Pragma("unroll") for (int k = 0; k < 2; ++k) \
;         acc[ai][bj][m][n] = __builtin_amdgcn_mfma_f32_16x16x32_bf16(Bt[n][k], At[m][k], acc[ai][bj][m][n], 0, 0, 0); __builtin_amdgcn_s_setprio(0); } while (0)
; #define PG8_WAIT_V(n) asm volatile("s_waitcnt vmcnt(" #n ")" ::: "memory")
; #define PG8_WAIT_L(n) asm volatile("s_waitcnt lgkmcnt(" #n ")" ::: "memory")
; #define PG8_BAR __builtin_amdgcn_s_barrier()
; #define PG8_SCHED __builtin_amdgcn_sched_barrier(0)
; template <class Epi, class Sched, bool ALIGN_EPI = false, bool SP2 = false>
; __device__ __forceinline__ void gemm_phase(PG8_LAS unsigned char* lds, const Gemm g, const Sched& S, const Epi& E) {
;     ...
;         for (int t = 0; t < nt; t += 2) {
;             if constexpr (Epi::PF_TRIPS > 0) { if (t == nt - 2 * Epi::PF_TRIPS) E.prefetch(cur, tid, lds + STAGE_BYTES + wid * 512); }
;             const bool last = (t == nt - 2);
;             const char* a1 = cA + (size_t)(t + 1) * kstep;
;             const char* a2 = last ? nA : cA + (size_t)(t + 2) * kstep; const char* b2 = last ? nB : cB + (size_t)(t + 2) * kstep;
;             const char* a3 = a2 + kstep; const char* b3 = b2 + kstep;
;     ...
;             PG8_LDA(At, 1, 1); PG8_STAGE(PG8_SB(1, 0), b3, voffB); PG8_STAGE(PG8_SB(1, 1), b3 + hstep, voffB); PG8_STAGE(PG8_SA(1, 0), a3, voffA);
;             PG8_WAIT_V(8); PG8_WAIT_L(0); PG8_BAR; PG8_MMA(1, 0, At, B0); PG8_MMA(1, 1, At, B1); PG8_BAR; PG8_SCHED;
	s_add_i32 s50, s69, s52
	v_lshl_add_u64 v[142:143], v[142:143], 0, s[40:41]
	s_mov_b32 m0, s50
	s_nop 0
	global_load_lds_dwordx4 v[142:143], off
	s_add_i32 m0, s50, 0x2000
	s_add_u32 s48, s48, 0x40080
	v_lshl_add_u64 v[142:143], v[146:147], 0, s[40:41]
	s_addc_u32 s49, s49, 0
	s_add_i32 s50, s70, s52
	global_load_lds_dwordx4 v[142:143], off
	v_lshl_add_u64 v[142:143], s[48:49], 0, v[134:135]
	s_mov_b32 m0, s50
	s_nop 0
	global_load_lds_dwordx4 v[142:143], off
	v_lshl_add_u64 v[142:143], s[48:49], 0, v[130:131]
	s_add_i32 m0, s50, 0x2000
	s_nop 0
	global_load_lds_dwordx4 v[142:143], off
	v_lshl_add_u64 v[142:143], v[200:201], 0, s[40:41]
	s_mov_b32 m0, s59
	s_nop 0
	global_load_lds_dwordx4 v[142:143], off
	v_lshl_add_u64 v[142:143], v[236:237], 0, s[40:41]
	s_mov_b32 m0, s60
	s_nop 0
	global_load_lds_dwordx4 v[142:143], off
	ds_read_b128 v[196:199], v149 offset:49152
	ds_read_b128 v[208:211], v149 offset:50176
	ds_read_b128 v[212:215], v149 offset:51200
	ds_read_b128 v[216:219], v149 offset:52224
	ds_read_b128 v[220:223], v149 offset:53248
	ds_read_b128 v[224:227], v149 offset:54272
	ds_read_b128 v[228:231], v149 offset:55296
	ds_read_b128 v[232:235], v149 offset:56320
	s_waitcnt vmcnt(8)
	s_waitcnt lgkmcnt(0)
	s_barrier
	s_setprio 1
	s_waitcnt lgkmcnt(0)
	v_mfma_f32_16x16x32_bf16 v[60:63], v[150:153], v[196:199], v[60:63]
	v_mfma_f32_16x16x32_bf16 v[56:59], v[158:161], v[196:199], v[56:59]
	v_mfma_f32_16x16x32_bf16 v[48:51], v[150:153], v[212:215], v[48:51]
	v_mfma_f32_16x16x32_bf16 v[40:43], v[158:161], v[212:215], v[40:43]
	v_mfma_f32_16x16x32_bf16 v[32:35], v[150:153], v[220:223], v[32:35]
	v_mfma_f32_16x16x32_bf16 v[24:27], v[158:161], v[220:223], v[24:27]
	v_mfma_f32_16x16x32_bf16 v[16:19], v[150:153], v[228:231], v[16:19]
	v_mfma_f32_16x16x32_bf16 v[8:11], v[158:161], v[228:231], v[8:11]
	v_mfma_f32_16x16x32_bf16 v[60:63], v[154:157], v[208:211], v[60:63]
	v_mfma_f32_16x16x32_bf16 v[56:59], v[176:179], v[208:211], v[56:59]
	v_mfma_f32_16x16x32_bf16 v[48:51], v[154:157], v[216:219], v[48:51]
	v_mfma_f32_16x16x32_bf16 v[40:43], v[176:179], v[216:219], v[40:43]
	v_mfma_f32_16x16x32_bf16 v[32:35], v[154:157], v[224:227], v[32:35]
	v_mfma_f32_16x16x32_bf16 v[24:27], v[176:179], v[224:227], v[24:27]
	v_mfma_f32_16x16x32_bf16 v[16:19], v[154:157], v[232:235], v[16:19]
	v_mfma_f32_16x16x32_bf16 v[8:11], v[176:179], v[232:235], v[8:11]
	s_setprio 0
	s_setprio 1
	v_mfma_f32_16x16x32_bf16 v[52:55], v[180:183], v[196:199], v[52:55]
	v_mfma_f32_16x16x32_bf16 v[44:47], v[188:191], v[196:199], v[44:47]
	v_mfma_f32_16x16x32_bf16 v[36:39], v[180:183], v[212:215], v[36:39]
	v_mfma_f32_16x16x32_bf16 v[28:31], v[188:191], v[212:215], v[28:31]
	v_mfma_f32_16x16x32_bf16 v[20:23], v[180:183], v[220:223], v[20:23]
	v_mfma_f32_16x16x32_bf16 v[12:15], v[188:191], v[220:223], v[12:15]
	v_mfma_f32_16x16x32_bf16 v[4:7], v[180:183], v[228:231], v[4:7]
	v_mfma_f32_16x16x32_bf16 v[0:3], v[188:191], v[228:231], v[0:3]
	v_mfma_f32_16x16x32_bf16 v[52:55], v[184:187], v[208:211], v[52:55]
	v_mfma_f32_16x16x32_bf16 v[44:47], v[192:195], v[208:211], v[44:47]
	v_mfma_f32_16x16x32_bf16 v[36:39], v[184:187], v[216:219], v[36:39]
	v_mfma_f32_16x16x32_bf16 v[28:31], v[192:195], v[216:219], v[28:31]
	v_mfma_f32_16x16x32_bf16 v[20:23], v[184:187], v[224:227], v[20:23]
	v_mfma_f32_16x16x32_bf16 v[12:15], v[192:195], v[224:227], v[12:15]
	v_mfma_f32_16x16x32_bf16 v[4:7], v[184:187], v[232:235], v[4:7]
	v_mfma_f32_16x16x32_bf16 v[0:3], v[192:195], v[232:235], v[0:3]
	s_setprio 0
	s_barrier
	s_add_i32 s68, s68, 2
	s_add_u32 s46, s46, 0x100
	s_addc_u32 s47, s47, 0
	s_add_u32 s66, s66, 0x100
	s_addc_u32 s67, s67, 0
	s_cmp_gt_u32 s68, 13
	s_cbranch_scc0 .LBB0_129
	s_and_b64 vcc, exec, s[14:15]
	s_cbranch_vccz .LBB0_132
	s_barrier

; #define PG8_STAGE(bufoff, gbase, voff) do { _Pragma("unroll") for (int _i = 0; _i < 2; ++_i) \
;         __builtin_amdgcn_global_load_lds((const unsigned*)((const char*)(gbase) + (voff)[_i]), (PG8_LAS unsigned*)(lds + (bufoff) + ldsw + _i * 8192), 16, 0, 0); } while (0)
; #define PG8_LDA(dst, b, h) do { _Pragma("unroll") for (int m = 0; m < 4; ++m) _Pragma("unroll") for (int k = 0; k < 2; ++k) dst[m][k] = *(const PG8_LAS bf16x8*)(lds + PG8_SA(b, h) + aoff + m * 2048 + k * 1024); } while (0)
; #define PG8_LDB(dst, b, h) do { _Pragma("unroll") for (int n = 0; n < 2; ++n) _Pragma("unroll") for (int k = 0; k < 2; ++k) dst[n][k] = *(const PG8_LAS bf16x8*)(lds + PG8_SB(b, h) + boff + n * 2048 + k * 1024); } while (0)
; #define PG8_MMA(ai, bj, At, Bt) do { __builtin_amdgcn_s_setprio(1); _Pragma("unroll") for (int m = 0; m < 4; ++m) _Pragma("unroll") for (int n = 0; n < 2; ++n) _Pragma("unroll") for (int k = 0; k < 2; ++k) \
;         acc[ai][bj][m][n] = __builtin_amdgcn_mfma_f32_16x16x32_bf16(Bt[n][k], At[m][k], acc[ai][bj][m][n], 0, 0, 0); __builtin_amdgcn_s_setprio(0); } while (0)
; #define PG8_WAIT_V(n) asm volatile("s_waitcnt vmcnt(" #n ")" ::: "memory")
; #define PG8_WAIT_L(n) asm volatile("s_waitcnt lgkmcnt(" #n ")" ::: "memory")
; template <class Epi, class Sched, bool ALIGN_EPI = false, bool SP2 = false>
; __device__ __forceinline__ void gemm_phase(PG8_LAS unsigned char* lds, const Gemm g, const Sched& S, const Epi& E) {
;     ...
;             const bool last = (t == nt - 2);
;             const char* a1 = cA + (size_t)(t + 1) * kstep;
;             const char* a2 = last ? nA : cA + (size_t)(t + 2) * kstep; const char* b2 = last ? nB : cB + (size_t)(t + 2) * kstep;
;             const char* a3 = a2 + kstep; const char* b3 = b2 + kstep;
;             if (last && has_next) S.a_ready(nxt);
;             if constexpr (SP2) {
;             PG8_LDB(B0, 0, 0); PG8_LDB(B1, 0, 1); PG8_SCHED; PG8_LDA(At, 0, 0); PG8_STAGE(PG8_SA(1, 1), a1 + hstep, voffA);
;             PG8_WAIT_V(8); PG8_WAIT_L(0); PG8_BAR; PG8_MMA(0, 0, At, B0); PG8_MMA(0, 1, At, B1); PG8_BAR; PG8_SCHED;
;             PG8_LDA(At, 0, 1); PG8_STAGE(PG8_SB(0, 0), b2, voffB); PG8_STAGE(PG8_SB(0, 1), b2 + hstep, voffB); PG8_STAGE(PG8_SA(0, 0), a2, voffA);
;             PG8_WAIT_V(8); PG8_WAIT_L(0); PG8_BAR; PG8_MMA(1, 0, At, B0); PG8_MMA(1, 1, At, B1); PG8_BAR; PG8_SCHED;
.LBB0_159:
	s_add_u32 s48, s6, 0xfffc0080
	s_addc_u32 s49, s7, -1
	s_add_i32 s71, 0, 0x10000
	s_cmp_eq_u32 s70, 12
	s_cselect_b32 s51, s5, s49
	s_cselect_b32 s50, s17, s48
	s_cselect_b32 s49, s19, s69
	s_cselect_b32 s48, s67, s68
	s_add_i32 s74, 0, 0x14000
	v_add_u32_e32 v142, s71, v199
	v_add_u32_e32 v158, s74, v199
	ds_read_b128 v[130:133], v142
	ds_read_b128 v[134:137], v142 offset:1024
	ds_read_b128 v[138:141], v142 offset:2048
	s_waitcnt lgkmcnt(0)
	ds_read_b128 v[142:145], v142 offset:3072
	ds_read_b128 v[146:149], v158
	ds_read_b128 v[150:153], v158 offset:1024
	ds_read_b128 v[154:157], v158 offset:2048
	ds_read_b128 v[158:161], v158 offset:3072
	v_lshl_add_u64 v[196:197], s[6:7], 0, v[184:185]
	s_add_i32 m0, s11, 0xc000
	ds_read_b128 v[188:191], v200
	ds_read_b128 v[192:195], v200 offset:1024
	ds_read_b128 v[208:211], v200 offset:2048
	ds_read_b128 v[212:215], v200 offset:3072
	ds_read_b128 v[216:219], v200 offset:4096
	ds_read_b128 v[220:223], v200 offset:5120
	ds_read_b128 v[224:227], v200 offset:6144
	ds_read_b128 v[228:231], v200 offset:7168
	global_load_lds_dwordx4 v[196:197], off
	v_lshl_add_u64 v[196:197], s[6:7], 0, v[186:187]
	s_add_i32 m0, s11, 0xe000
	s_nop 0
	global_load_lds_dwordx4 v[196:197], off
	s_waitcnt vmcnt(8)
	s_waitcnt lgkmcnt(0)
	s_barrier
	s_setprio 1
	s_waitcnt lgkmcnt(0)
	v_mfma_f32_16x16x32_bf16 v[126:129], v[130:133], v[188:191], v[126:129]
	v_mfma_f32_16x16x32_bf16 v[122:125], v[138:141], v[188:191], v[122:125]
	v_mfma_f32_16x16x32_bf16 v[110:113], v[130:133], v[208:211], v[110:113]
	v_mfma_f32_16x16x32_bf16 v[106:109], v[138:141], v[208:211], v[106:109]
	v_mfma_f32_16x16x32_bf16 v[94:97], v[130:133], v[216:219], v[94:97]
	v_mfma_f32_16x16x32_bf16 v[90:93], v[138:141], v[216:219], v[90:93]
	v_mfma_f32_16x16x32_bf16 v[76:79], v[130:133], v[224:227], v[76:79]
	v_mfma_f32_16x16x32_bf16 v[72:75], v[138:141], v[224:227], v[72:75]
	v_mfma_f32_16x16x32_bf16 v[126:129], v[134:137], v[192:195], v[126:129]
	v_mfma_f32_16x16x32_bf16 v[122:125], v[142:145], v[192:195], v[122:125]
	v_mfma_f32_16x16x32_bf16 v[110:113], v[134:137], v[212:215], v[110:113]
	v_mfma_f32_16x16x32_bf16 v[106:109], v[142:145], v[212:215], v[106:109]
	v_mfma_f32_16x16x32_bf16 v[94:97], v[134:137], v[220:223], v[94:97]
	v_mfma_f32_16x16x32_bf16 v[90:93], v[142:145], v[220:223], v[90:93]
	v_mfma_f32_16x16x32_bf16 v[76:79], v[134:137], v[228:231], v[76:79]
	v_mfma_f32_16x16x32_bf16 v[72:75], v[142:145], v[228:231], v[72:75]
	s_setprio 0
	s_setprio 1
	v_mfma_f32_16x16x32_bf16 v[118:121], v[146:149], v[188:191], v[118:121]
	v_mfma_f32_16x16x32_bf16 v[114:117], v[154:157], v[188:191], v[114:117]
	v_mfma_f32_16x16x32_bf16 v[102:105], v[146:149], v[208:211], v[102:105]
	v_mfma_f32_16x16x32_bf16 v[98:101], v[154:157], v[208:211], v[98:101]
	v_mfma_f32_16x16x32_bf16 v[86:89], v[146:149], v[216:219], v[86:89]
	v_mfma_f32_16x16x32_bf16 v[82:85], v[154:157], v[216:219], v[82:85]
	v_mfma_f32_16x16x32_bf16 v[68:71], v[146:149], v[224:227], v[68:71]
	v_mfma_f32_16x16x32_bf16 v[64:67], v[154:157], v[224:227], v[64:67]
	v_mfma_f32_16x16x32_bf16 v[118:121], v[150:153], v[192:195], v[118:121]
	v_mfma_f32_16x16x32_bf16 v[114:117], v[158:161], v[192:195], v[114:117]
	v_mfma_f32_16x16x32_bf16 v[102:105], v[150:153], v[212:215], v[102:105]
	v_mfma_f32_16x16x32_bf16 v[98:101], v[158:161], v[212:215], v[98:101]
	v_mfma_f32_16x16x32_bf16 v[86:89], v[150:153], v[220:223], v[86:89]
	v_mfma_f32_16x16x32_bf16 v[82:85], v[158:161], v[220:223], v[82:85]
	v_mfma_f32_16x16x32_bf16 v[68:71], v[150:153], v[228:231], v[68:71]
	v_mfma_f32_16x16x32_bf16 v[64:67], v[158:161], v[228:231], v[64:67]
	s_setprio 0
	s_barrier
	s_add_i32 s71, s71, s54
	v_lshl_add_u64 v[196:197], s[48:49], 0, v[178:179]
	s_mov_b32 m0, s71
	s_nop 0
	global_load_lds_dwordx4 v[196:197], off
	s_add_i32 m0, s71, 0x2000
	s_add_u32 s72, s48, 0x40000
	v_lshl_add_u64 v[232:233], s[48:49], 0, v[182:183]
	s_addc_u32 s73, s49, 0
	s_add_i32 s71, s74, s54
	global_load_lds_dwordx4 v[232:233], off
	v_lshl_add_u64 v[234:235], s[72:73], 0, v[178:179]
	s_mov_b32 m0, s71
	v_lshl_add_u64 v[236:237], s[50:51], 0, v[180:181]
	global_load_lds_dwordx4 v[234:235], off
	v_lshl_add_u64 v[234:235], s[72:73], 0, v[182:183]
	s_add_i32 m0, s71, 0x2000
	s_nop 0
	global_load_lds_dwordx4 v[234:235], off
	v_lshl_add_u64 v[234:235], s[50:51], 0, v[176:177]
	s_mov_b32 m0, s11
	s_nop 0
	global_load_lds_dwordx4 v[234:235], off
	s_mov_b32 m0, s55
	s_nop 0
	global_load_lds_dwordx4 v[236:237], off
	ds_read_b128 v[188:191], v200 offset:16384
	ds_read_b128 v[192:195], v200 offset:17408
	ds_read_b128 v[208:211], v200 offset:18432
	ds_read_b128 v[212:215], v200 offset:19456
	ds_read_b128 v[216:219], v200 offset:20480
	ds_read_b128 v[220:223], v200 offset:21504
	ds_read_b128 v[224:227], v200 offset:22528
	ds_read_b128 v[228:231], v200 offset:23552
	s_waitcnt vmcnt(8)
	s_waitcnt lgkmcnt(0)
	s_barrier
; #define PG8_STAGE(bufoff, gbase, voff) do { _Pragma("unroll") for (int _i = 0; _i < 2; ++_i) \
;         __builtin_amdgcn_global_load_lds((const unsigned*)((const char*)(gbase) + (voff)[_i]), (PG8_LAS unsigned*)(lds + (bufoff) + ldsw + _i * 8192), 16, 0, 0); } while (0)
; #define PG8_LDA(dst, b, h) do { _Pragma("unroll") for (int m = 0; m < 4; ++m) _Pragma("unroll") for (int k = 0; k < 2; ++k) dst[m][k] = *(const PG8_LAS bf16x8*)(lds + PG8_SA(b, h) + aoff + m * 2048 + k * 1024); } while (0)
; #define PG8_LDB(dst, b, h) do { _Pragma("unroll") for (int n = 0; n < 2; ++n) _Pragma("unroll") for (int k = 0; k < 2; ++k) dst[n][k] = *(const PG8_LAS bf16x8*)(lds + PG8_SB(b, h) + boff + n * 2048 + k * 1024); } while (0)
; #define PG8_MMA(ai, bj, At, Bt) do { __builtin_amdgcn_s_setprio(1); _Pragma("unroll") for (int m = 0; m < 4; ++m) _Pragma("unroll") for (int n = 0; n < 2; ++n) _Pragma("unroll") for (int k = 0; k < 2; ++k) \
;         acc[ai][bj][m][n] = __builtin_amdgcn_mfma_f32_16x16x32_bf16(Bt[n][k], At[m][k], acc[ai][bj][m][n], 0, 0, 0); __builtin_amdgcn_s_setprio(0); } while (0)
; #define PG8_WAIT_V(n) asm volatile("s_waitcnt vmcnt(" #n ")" ::: "memory")
; #define PG8_WAIT_L(n) asm volatile("s_waitcnt lgkmcnt(" #n ")" ::: "memory")
; #define PG8_BAR __builtin_amdgcn_s_barrier()
; #define PG8_SCHED __builtin_amdgcn_sched_barrier(0)
; template <class Epi, class Sched, bool ALIGN_EPI = false, bool SP2 = false>
; __device__ __forceinline__ void gemm_phase(PG8_LAS unsigned char* lds, const Gemm g, const Sched& S, const Epi& E) {
;     ...
;             PG8_WAIT_V(8); PG8_WAIT_L(0); PG8_BAR; PG8_MMA(1, 0, At, B0); PG8_MMA(1, 1, At, B1); PG8_BAR; PG8_SCHED;
;             PG8_LDB(B0, 1, 0); PG8_LDB(B1, 1, 1); PG8_SCHED; PG8_LDA(At, 1, 0); PG8_STAGE(PG8_SA(0, 1), a2 + hstep, voffA);
;             PG8_WAIT_V(8); PG8_WAIT_L(0); PG8_BAR; PG8_MMA(0, 0, At, B0); PG8_MMA(0, 1, At, B1); PG8_BAR; PG8_SCHED;
	s_setprio 1
	s_waitcnt lgkmcnt(0)
	v_mfma_f32_16x16x32_bf16 v[60:63], v[130:133], v[188:191], v[60:63]
	v_mfma_f32_16x16x32_bf16 v[56:59], v[138:141], v[188:191], v[56:59]
	v_mfma_f32_16x16x32_bf16 v[44:47], v[130:133], v[208:211], v[44:47]
	v_mfma_f32_16x16x32_bf16 v[40:43], v[138:141], v[208:211], v[40:43]
	v_mfma_f32_16x16x32_bf16 v[28:31], v[130:133], v[216:219], v[28:31]
	v_mfma_f32_16x16x32_bf16 v[24:27], v[138:141], v[216:219], v[24:27]
	v_mfma_f32_16x16x32_bf16 v[12:15], v[130:133], v[224:227], v[12:15]
	v_mfma_f32_16x16x32_bf16 v[8:11], v[138:141], v[224:227], v[8:11]
	v_mfma_f32_16x16x32_bf16 v[60:63], v[134:137], v[192:195], v[60:63]
	v_mfma_f32_16x16x32_bf16 v[56:59], v[142:145], v[192:195], v[56:59]
	v_mfma_f32_16x16x32_bf16 v[44:47], v[134:137], v[212:215], v[44:47]
	v_mfma_f32_16x16x32_bf16 v[40:43], v[142:145], v[212:215], v[40:43]
	v_mfma_f32_16x16x32_bf16 v[28:31], v[134:137], v[220:223], v[28:31]
	v_mfma_f32_16x16x32_bf16 v[24:27], v[142:145], v[220:223], v[24:27]
	v_mfma_f32_16x16x32_bf16 v[12:15], v[134:137], v[228:231], v[12:15]
	v_mfma_f32_16x16x32_bf16 v[8:11], v[142:145], v[228:231], v[8:11]
	s_setprio 0
	s_setprio 1
	v_mfma_f32_16x16x32_bf16 v[52:55], v[146:149], v[188:191], v[52:55]
	v_mfma_f32_16x16x32_bf16 v[48:51], v[154:157], v[188:191], v[48:51]
	v_mfma_f32_16x16x32_bf16 v[36:39], v[146:149], v[208:211], v[36:39]
	v_mfma_f32_16x16x32_bf16 v[32:35], v[154:157], v[208:211], v[32:35]
	v_mfma_f32_16x16x32_bf16 v[20:23], v[146:149], v[216:219], v[20:23]
	v_mfma_f32_16x16x32_bf16 v[16:19], v[154:157], v[216:219], v[16:19]
	v_mfma_f32_16x16x32_bf16 v[4:7], v[146:149], v[224:227], v[4:7]
	v_mfma_f32_16x16x32_bf16 v[0:3], v[154:157], v[224:227], v[0:3]
	v_mfma_f32_16x16x32_bf16 v[52:55], v[150:153], v[192:195], v[52:55]
	v_mfma_f32_16x16x32_bf16 v[48:51], v[158:161], v[192:195], v[48:51]
	v_mfma_f32_16x16x32_bf16 v[36:39], v[150:153], v[212:215], v[36:39]
	v_mfma_f32_16x16x32_bf16 v[32:35], v[158:161], v[212:215], v[32:35]
	v_mfma_f32_16x16x32_bf16 v[20:23], v[150:153], v[220:223], v[20:23]
	v_mfma_f32_16x16x32_bf16 v[16:19], v[158:161], v[220:223], v[16:19]
	v_mfma_f32_16x16x32_bf16 v[4:7], v[150:153], v[228:231], v[4:7]
	v_mfma_f32_16x16x32_bf16 v[0:3], v[158:161], v[228:231], v[0:3]
	s_setprio 0
	s_barrier
	s_add_i32 s71, 0, 0x18000
	s_add_i32 s72, 0, 0x1c000
	v_add_u32_e32 v142, s71, v199
	v_add_u32_e32 v158, s72, v199
	ds_read_b128 v[130:133], v142
	ds_read_b128 v[134:137], v142 offset:1024
	ds_read_b128 v[138:141], v142 offset:2048
	ds_read_b128 v[142:145], v142 offset:3072
	ds_read_b128 v[146:149], v158
	ds_read_b128 v[150:153], v158 offset:1024
	ds_read_b128 v[154:157], v158 offset:2048
	ds_read_b128 v[158:161], v158 offset:3072
	s_add_u32 s50, s50, 0x40000
	s_addc_u32 s51, s51, 0
	s_mov_b32 m0, s56
	v_lshl_add_u64 v[238:239], s[50:51], 0, v[176:177]
	ds_read_b128 v[188:191], v200 offset:32768
	ds_read_b128 v[192:195], v200 offset:33792
	ds_read_b128 v[208:211], v200 offset:34816
	ds_read_b128 v[212:215], v200 offset:35840
	ds_read_b128 v[216:219], v200 offset:36864
	ds_read_b128 v[220:223], v200 offset:37888
	ds_read_b128 v[224:227], v200 offset:38912
	ds_read_b128 v[228:231], v200 offset:39936
	global_load_lds_dwordx4 v[238:239], off
	v_lshl_add_u64 v[238:239], s[50:51], 0, v[180:181]
	s_mov_b32 m0, s57
	s_nop 0
	global_load_lds_dwordx4 v[238:239], off
	s_waitcnt vmcnt(8)
	s_waitcnt lgkmcnt(0)
	s_barrier
	s_setprio 1
	s_waitcnt lgkmcnt(0)
	v_mfma_f32_16x16x32_bf16 v[126:129], v[130:133], v[188:191], v[126:129]
	v_mfma_f32_16x16x32_bf16 v[122:125], v[138:141], v[188:191], v[122:125]
	v_mfma_f32_16x16x32_bf16 v[110:113], v[130:133], v[208:211], v[110:113]
	v_mfma_f32_16x16x32_bf16 v[106:109], v[138:141], v[208:211], v[106:109]
	v_mfma_f32_16x16x32_bf16 v[94:97], v[130:133], v[216:219], v[94:97]
	v_mfma_f32_16x16x32_bf16 v[90:93], v[138:141], v[216:219], v[90:93]
	v_mfma_f32_16x16x32_bf16 v[76:79], v[130:133], v[224:227], v[76:79]
	v_mfma_f32_16x16x32_bf16 v[72:75], v[138:141], v[224:227], v[72:75]
	v_mfma_f32_16x16x32_bf16 v[126:129], v[134:137], v[192:195], v[126:129]
	v_mfma_f32_16x16x32_bf16 v[122:125], v[142:145], v[192:195], v[122:125]
	v_mfma_f32_16x16x32_bf16 v[110:113], v[134:137], v[212:215], v[110:113]
	v_mfma_f32_16x16x32_bf16 v[106:109], v[142:145], v[212:215], v[106:109]
	v_mfma_f32_16x16x32_bf16 v[94:97], v[134:137], v[220:223], v[94:97]
	v_mfma_f32_16x16x32_bf16 v[90:93], v[142:145], v[220:223], v[90:93]
	v_mfma_f32_16x16x32_bf16 v[76:79], v[134:137], v[228:231], v[76:79]
	v_mfma_f32_16x16x32_bf16 v[72:75], v[142:145], v[228:231], v[72:75]
	s_setprio 0
	s_setprio 1
	v_mfma_f32_16x16x32_bf16 v[118:121], v[146:149], v[188:191], v[118:121]
	v_mfma_f32_16x16x32_bf16 v[114:117], v[154:157], v[188:191], v[114:117]
	v_mfma_f32_16x16x32_bf16 v[102:105], v[146:149], v[208:211], v[102:105]
	v_mfma_f32_16x16x32_bf16 v[98:101], v[154:157], v[208:211], v[98:101]
	v_mfma_f32_16x16x32_bf16 v[86:89], v[146:149], v[216:219], v[86:89]
	v_mfma_f32_16x16x32_bf16 v[82:85], v[154:157], v[216:219], v[82:85]
	v_mfma_f32_16x16x32_bf16 v[68:71], v[146:149], v[224:227], v[68:71]
	v_mfma_f32_16x16x32_bf16 v[64:67], v[154:157], v[224:227], v[64:67]
	v_mfma_f32_16x16x32_bf16 v[118:121], v[150:153], v[192:195], v[118:121]
	v_mfma_f32_16x16x32_bf16 v[114:117], v[158:161], v[192:195], v[114:117]
	v_mfma_f32_16x16x32_bf16 v[102:105], v[150:153], v[212:215], v[102:105]
	v_mfma_f32_16x16x32_bf16 v[98:101], v[158:161], v[212:215], v[98:101]
	v_mfma_f32_16x16x32_bf16 v[86:89], v[150:153], v[220:223], v[86:89]
	v_mfma_f32_16x16x32_bf16 v[82:85], v[158:161], v[220:223], v[82:85]
	v_mfma_f32_16x16x32_bf16 v[68:71], v[150:153], v[228:231], v[68:71]
	v_mfma_f32_16x16x32_bf16 v[64:67], v[158:161], v[228:231], v[64:67]
	s_setprio 0
	s_barrier
; #define PG8_STAGE(bufoff, gbase, voff) do { _Pragma("unroll") for (int _i = 0; _i < 2; ++_i) \
;         __builtin_amdgcn_global_load_lds((const unsigned*)((const char*)(gbase) + (voff)[_i]), (PG8_LAS unsigned*)(lds + (bufoff) + ldsw + _i * 8192), 16, 0, 0); } while (0)
; #define PG8_LDA(dst, b, h) do { _Pragma("unroll") for (int m = 0; m < 4; ++m) _Pragma("unroll") for (int k = 0; k < 2; ++k) dst[m][k] = *(const PG8_LAS bf16x8*)(lds + PG8_SA(b, h) + aoff + m * 2048 + k * 1024); } while (0)
; #define PG8_MMA(ai, bj, At, Bt) do { __builtin_amdgcn_s_setprio(1); _Pragma("unroll") for (int m = 0; m < 4; ++m) _Pragma("unroll") for (int n = 0; n < 2; ++n) _Pragma("unroll") for (int k = 0; k < 2; ++k) \
;         acc[ai][bj][m][n] = __builtin_amdgcn_mfma_f32_16x16x32_bf16(Bt[n][k], At[m][k], acc[ai][bj][m][n], 0, 0, 0); __builtin_amdgcn_s_setprio(0); } while (0)
; #define PG8_WAIT_V(n) asm volatile("s_waitcnt vmcnt(" #n ")" ::: "memory")
; #define PG8_WAIT_L(n) asm volatile("s_waitcnt lgkmcnt(" #n ")" ::: "memory")
; #define PG8_BAR __builtin_amdgcn_s_barrier()
; #define PG8_SCHED __builtin_amdgcn_sched_barrier(0)
; template <class Epi, class Sched, bool ALIGN_EPI = false, bool SP2 = false>
; __device__ __forceinline__ void gemm_phase(PG8_LAS unsigned char* lds, const Gemm g, const Sched& S, const Epi& E) {
;     ...
;             PG8_LDA(At, 1, 1); PG8_STAGE(PG8_SB(1, 0), b3, voffB); PG8_STAGE(PG8_SB(1, 1), b3 + hstep, voffB); PG8_STAGE(PG8_SA(1, 0), a3, voffA);
;             PG8_WAIT_V(8); PG8_WAIT_L(0); PG8_BAR; PG8_MMA(1, 0, At, B0); PG8_MMA(1, 1, At, B1); PG8_BAR; PG8_SCHED;
;     ...
;         if constexpr (ALIGN_EPI) { if (wr == 0) PG8_BAR; }
	s_add_i32 s50, s71, s54
	v_lshl_add_u64 v[196:197], v[196:197], 0, s[40:41]
	s_mov_b32 m0, s50
	s_nop 0
	global_load_lds_dwordx4 v[196:197], off
	s_add_i32 m0, s50, 0x2000
	s_add_u32 s48, s48, 0x40080
	v_lshl_add_u64 v[196:197], v[232:233], 0, s[40:41]
	s_addc_u32 s49, s49, 0
	s_add_i32 s50, s72, s54
	global_load_lds_dwordx4 v[196:197], off
	v_lshl_add_u64 v[196:197], s[48:49], 0, v[178:179]
	s_mov_b32 m0, s50
	s_nop 0
	global_load_lds_dwordx4 v[196:197], off
	v_lshl_add_u64 v[196:197], s[48:49], 0, v[182:183]
	s_add_i32 m0, s50, 0x2000
	s_nop 0
	global_load_lds_dwordx4 v[196:197], off
	v_lshl_add_u64 v[196:197], v[234:235], 0, s[40:41]
	s_mov_b32 m0, s61
	s_nop 0
	global_load_lds_dwordx4 v[196:197], off
	v_lshl_add_u64 v[196:197], v[236:237], 0, s[40:41]
	s_mov_b32 m0, s62
	s_nop 0
	global_load_lds_dwordx4 v[196:197], off
	ds_read_b128 v[188:191], v200 offset:49152
	ds_read_b128 v[192:195], v200 offset:50176
	ds_read_b128 v[208:211], v200 offset:51200
	ds_read_b128 v[212:215], v200 offset:52224
	ds_read_b128 v[216:219], v200 offset:53248
	ds_read_b128 v[220:223], v200 offset:54272
	ds_read_b128 v[224:227], v200 offset:55296
	ds_read_b128 v[228:231], v200 offset:56320
	s_waitcnt vmcnt(8)
	s_waitcnt lgkmcnt(0)
	s_barrier
	s_setprio 1
	s_waitcnt lgkmcnt(0)
	v_mfma_f32_16x16x32_bf16 v[60:63], v[130:133], v[188:191], v[60:63]
	v_mfma_f32_16x16x32_bf16 v[56:59], v[138:141], v[188:191], v[56:59]
	v_mfma_f32_16x16x32_bf16 v[44:47], v[130:133], v[208:211], v[44:47]
	v_mfma_f32_16x16x32_bf16 v[40:43], v[138:141], v[208:211], v[40:43]
	v_mfma_f32_16x16x32_bf16 v[28:31], v[130:133], v[216:219], v[28:31]
	v_mfma_f32_16x16x32_bf16 v[24:27], v[138:141], v[216:219], v[24:27]
	v_mfma_f32_16x16x32_bf16 v[12:15], v[130:133], v[224:227], v[12:15]
	v_mfma_f32_16x16x32_bf16 v[8:11], v[138:141], v[224:227], v[8:11]
	v_mfma_f32_16x16x32_bf16 v[60:63], v[134:137], v[192:195], v[60:63]
	v_mfma_f32_16x16x32_bf16 v[56:59], v[142:145], v[192:195], v[56:59]
	v_mfma_f32_16x16x32_bf16 v[44:47], v[134:137], v[212:215], v[44:47]
	v_mfma_f32_16x16x32_bf16 v[40:43], v[142:145], v[212:215], v[40:43]
	v_mfma_f32_16x16x32_bf16 v[28:31], v[134:137], v[220:223], v[28:31]
	v_mfma_f32_16x16x32_bf16 v[24:27], v[142:145], v[220:223], v[24:27]
	v_mfma_f32_16x16x32_bf16 v[12:15], v[134:137], v[228:231], v[12:15]
	v_mfma_f32_16x16x32_bf16 v[8:11], v[142:145], v[228:231], v[8:11]
	s_setprio 0
	s_setprio 1
	v_mfma_f32_16x16x32_bf16 v[52:55], v[146:149], v[188:191], v[52:55]
	v_mfma_f32_16x16x32_bf16 v[48:51], v[154:157], v[188:191], v[48:51]
	v_mfma_f32_16x16x32_bf16 v[36:39], v[146:149], v[208:211], v[36:39]
	v_mfma_f32_16x16x32_bf16 v[32:35], v[154:157], v[208:211], v[32:35]
	v_mfma_f32_16x16x32_bf16 v[20:23], v[146:149], v[216:219], v[20:23]
	v_mfma_f32_16x16x32_bf16 v[16:19], v[154:157], v[216:219], v[16:19]
	v_mfma_f32_16x16x32_bf16 v[4:7], v[146:149], v[224:227], v[4:7]
	v_mfma_f32_16x16x32_bf16 v[0:3], v[154:157], v[224:227], v[0:3]
	v_mfma_f32_16x16x32_bf16 v[52:55], v[150:153], v[192:195], v[52:55]
	v_mfma_f32_16x16x32_bf16 v[48:51], v[158:161], v[192:195], v[48:51]
	v_mfma_f32_16x16x32_bf16 v[36:39], v[150:153], v[212:215], v[36:39]
	v_mfma_f32_16x16x32_bf16 v[32:35], v[158:161], v[212:215], v[32:35]
	v_mfma_f32_16x16x32_bf16 v[20:23], v[150:153], v[220:223], v[20:23]
	v_mfma_f32_16x16x32_bf16 v[16:19], v[158:161], v[220:223], v[16:19]
	v_mfma_f32_16x16x32_bf16 v[4:7], v[150:153], v[228:231], v[4:7]
	v_mfma_f32_16x16x32_bf16 v[0:3], v[158:161], v[228:231], v[0:3]
	s_setprio 0
	s_barrier
	s_add_i32 s70, s70, 2
	s_add_u32 s6, s6, 0x100
	s_addc_u32 s7, s7, 0
	s_add_u32 s68, s68, 0x100
	s_addc_u32 s69, s69, 0
	s_cmp_gt_u32 s70, 13
	s_cbranch_scc0 .LBB0_159
	s_and_b64 vcc, exec, s[14:15]
	s_cbranch_vccz .LBB0_162
	s_barrier

; #define PG8_STAGE(bufoff, gbase, voff) do { _Pragma("unroll") for (int _i = 0; _i < 2; ++_i) \
;         __builtin_amdgcn_global_load_lds((const unsigned*)((const char*)(gbase) + (voff)[_i]), (PG8_LAS unsigned*)(lds + (bufoff) + ldsw + _i * 8192), 16, 0, 0); } while (0)
; #define PG8_LDA(dst, b, h) do { _Pragma("unroll") for (int m = 0; m < 4; ++m) _Pragma("unroll") for (int k = 0; k < 2; ++k) dst[m][k] = *(const PG8_LAS bf16x8*)(lds + PG8_SA(b, h) + aoff + m * 2048 + k * 1024); } while (0)
; #define PG8_LDB(dst, b, h) do { _Pragma("unroll") for (int n = 0; n < 2; ++n) _Pragma("unroll") for (int k = 0; k < 2; ++k) dst[n][k] = *(const PG8_LAS bf16x8*)(lds + PG8_SB(b, h) + boff + n * 2048 + k * 1024); } while (0)
; #define PG8_MMA(ai, bj, At, Bt) do { __builtin_amdgcn_s_setprio(1); _Pragma("unroll") for (int m = 0; m < 4; ++m) _Pragma("unroll") for (int n = 0; n < 2; ++n) _Pragma("unroll") for (int k = 0; k < 2; ++k) \
;         acc[ai][bj][m][n] = __builtin_amdgcn_mfma_f32_16x16x32_bf16(Bt[n][k], At[m][k], acc[ai][bj][m][n], 0, 0, 0); __builtin_amdgcn_s_setprio(0); } while (0)
; #define PG8_WAIT_V(n) asm volatile("s_waitcnt vmcnt(" #n ")" ::: "memory")
; #define PG8_WAIT_L(n) asm volatile("s_waitcnt lgkmcnt(" #n ")" ::: "memory")
; template <class Epi, class Sched, bool ALIGN_EPI = false, bool SP2 = false>
; __device__ __forceinline__ void gemm_phase(PG8_LAS unsigned char* lds, const Gemm g, const Sched& S, const Epi& E) {
;     ...
;             const bool last = (t == nt - 2);
;             const char* a1 = cA + (size_t)(t + 1) * kstep;
;             const char* a2 = last ? nA : cA + (size_t)(t + 2) * kstep; const char* b2 = last ? nB : cB + (size_t)(t + 2) * kstep;
;             const char* a3 = a2 + kstep; const char* b3 = b2 + kstep;
;             if (last && has_next) S.a_ready(nxt);
;             if constexpr (SP2) {
;             PG8_LDB(B0, 0, 0); PG8_LDB(B1, 0, 1); PG8_SCHED; PG8_LDA(At, 0, 0); PG8_STAGE(PG8_SA(1, 1), a1 + hstep, voffA);
;             PG8_WAIT_V(8); PG8_WAIT_L(0); PG8_BAR; PG8_MMA(0, 0, At, B0); PG8_MMA(0, 1, At, B1); PG8_BAR; PG8_SCHED;
;             PG8_LDA(At, 0, 1); PG8_STAGE(PG8_SB(0, 0), b2, voffB); PG8_STAGE(PG8_SB(0, 1), b2 + hstep, voffB); PG8_STAGE(PG8_SA(0, 0), a2, voffA);
;             PG8_WAIT_V(8); PG8_WAIT_L(0); PG8_BAR; PG8_MMA(1, 0, At, B0); PG8_MMA(1, 1, At, B1); PG8_BAR; PG8_SCHED;
.LBB0_383:
	s_add_i32 s73, s56, 2
	s_add_u32 s57, s44, s54
	s_addc_u32 s74, s45, s55
	s_add_u32 s75, s57, 0x100
	s_addc_u32 s57, s74, 0
	s_add_u32 s74, s47, s54
	s_addc_u32 s76, s49, s55
	s_add_i32 s77, 0, 0x10000
	s_cmp_eq_u32 s15, s56
	s_cselect_b32 s57, s5, s57
	s_cselect_b32 s56, s4, s75
	s_cselect_b32 s75, s43, s76
	s_cselect_b32 s74, s42, s74
	s_add_i32 s76, 0, 0x14000
	v_add_u32_e32 v146, s77, v209
	v_add_u32_e32 v188, s76, v209
	ds_read_b128 v[134:137], v146
	ds_read_b128 v[138:141], v146 offset:1024
	ds_read_b128 v[142:145], v146 offset:2048
	ds_read_b128 v[146:149], v146 offset:3072
	ds_read_b128 v[150:153], v188
	ds_read_b128 v[154:157], v188 offset:1024
	ds_read_b128 v[184:187], v188 offset:2048
	ds_read_b128 v[188:191], v188 offset:3072
	v_lshl_add_u64 v[200:201], v[130:131], 0, s[54:55]
	s_add_i32 m0, s58, 0xc000
	ds_read_b128 v[192:195], v211
	ds_read_b128 v[196:199], v211 offset:1024
	ds_read_b128 v[212:215], v211 offset:2048
	ds_read_b128 v[216:219], v211 offset:3072
	ds_read_b128 v[220:223], v211 offset:4096
	ds_read_b128 v[224:227], v211 offset:5120
	ds_read_b128 v[228:231], v211 offset:6144
	ds_read_b128 v[232:235], v211 offset:7168
	global_load_lds_dwordx4 v[200:201], off
	v_lshl_add_u64 v[200:201], v[132:133], 0, s[54:55]
	s_add_i32 m0, s58, 0xe000
	s_nop 0
	global_load_lds_dwordx4 v[200:201], off
	s_waitcnt vmcnt(8)
	s_waitcnt lgkmcnt(0)
	s_barrier
	s_setprio 1
	s_waitcnt lgkmcnt(0)
	v_mfma_f32_16x16x32_bf16 v[126:129], v[134:137], v[192:195], v[126:129]
	v_mfma_f32_16x16x32_bf16 v[122:125], v[142:145], v[192:195], v[122:125]
	v_mfma_f32_16x16x32_bf16 v[110:113], v[134:137], v[212:215], v[110:113]
	v_mfma_f32_16x16x32_bf16 v[106:109], v[142:145], v[212:215], v[106:109]
	v_mfma_f32_16x16x32_bf16 v[94:97], v[134:137], v[220:223], v[94:97]
	v_mfma_f32_16x16x32_bf16 v[90:93], v[142:145], v[220:223], v[90:93]
	v_mfma_f32_16x16x32_bf16 v[76:79], v[134:137], v[228:231], v[76:79]
	v_mfma_f32_16x16x32_bf16 v[72:75], v[142:145], v[228:231], v[72:75]
	v_mfma_f32_16x16x32_bf16 v[126:129], v[138:141], v[196:199], v[126:129]
	v_mfma_f32_16x16x32_bf16 v[122:125], v[146:149], v[196:199], v[122:125]
	v_mfma_f32_16x16x32_bf16 v[110:113], v[138:141], v[216:219], v[110:113]
	v_mfma_f32_16x16x32_bf16 v[106:109], v[146:149], v[216:219], v[106:109]
	v_mfma_f32_16x16x32_bf16 v[94:97], v[138:141], v[224:227], v[94:97]
	v_mfma_f32_16x16x32_bf16 v[90:93], v[146:149], v[224:227], v[90:93]
	v_mfma_f32_16x16x32_bf16 v[76:79], v[138:141], v[232:235], v[76:79]
	v_mfma_f32_16x16x32_bf16 v[72:75], v[146:149], v[232:235], v[72:75]
	s_setprio 0
	s_setprio 1
	v_mfma_f32_16x16x32_bf16 v[118:121], v[150:153], v[192:195], v[118:121]
	v_mfma_f32_16x16x32_bf16 v[114:117], v[184:187], v[192:195], v[114:117]
	v_mfma_f32_16x16x32_bf16 v[102:105], v[150:153], v[212:215], v[102:105]
	v_mfma_f32_16x16x32_bf16 v[98:101], v[184:187], v[212:215], v[98:101]
	v_mfma_f32_16x16x32_bf16 v[86:89], v[150:153], v[220:223], v[86:89]
	v_mfma_f32_16x16x32_bf16 v[82:85], v[184:187], v[220:223], v[82:85]
	v_mfma_f32_16x16x32_bf16 v[68:71], v[150:153], v[228:231], v[68:71]
	v_mfma_f32_16x16x32_bf16 v[64:67], v[184:187], v[228:231], v[64:67]
	v_mfma_f32_16x16x32_bf16 v[118:121], v[154:157], v[196:199], v[118:121]
	v_mfma_f32_16x16x32_bf16 v[114:117], v[188:191], v[196:199], v[114:117]
	v_mfma_f32_16x16x32_bf16 v[102:105], v[154:157], v[216:219], v[102:105]
	v_mfma_f32_16x16x32_bf16 v[98:101], v[188:191], v[216:219], v[98:101]
	v_mfma_f32_16x16x32_bf16 v[86:89], v[154:157], v[224:227], v[86:89]
	v_mfma_f32_16x16x32_bf16 v[82:85], v[188:191], v[224:227], v[82:85]
	v_mfma_f32_16x16x32_bf16 v[68:71], v[154:157], v[232:235], v[68:71]
	v_mfma_f32_16x16x32_bf16 v[64:67], v[188:191], v[232:235], v[64:67]
	s_setprio 0
	s_barrier
	s_add_i32 s77, s77, s39
	v_lshl_add_u64 v[200:201], s[74:75], 0, v[176:177]
	s_mov_b32 m0, s77
	s_nop 0
	global_load_lds_dwordx4 v[200:201], off
	s_add_i32 m0, s77, 0x2000
	v_lshl_add_u64 v[236:237], s[74:75], 0, v[158:159]
	s_add_u32 s74, s74, s14
	s_addc_u32 s75, s75, 0
	s_add_i32 s76, s76, s39
	global_load_lds_dwordx4 v[236:237], off
	v_lshl_add_u64 v[238:239], s[74:75], 0, v[176:177]
	s_mov_b32 m0, s76
	v_lshl_add_u64 v[240:241], s[74:75], 0, v[158:159]
	global_load_lds_dwordx4 v[238:239], off
	s_add_i32 m0, s76, 0x2000
	v_lshl_add_u64 v[242:243], s[56:57], 0, v[178:179]
	global_load_lds_dwordx4 v[240:241], off
	s_mov_b32 m0, s58
	v_lshl_add_u64 v[244:245], s[56:57], 0, v[160:161]
	global_load_lds_dwordx4 v[242:243], off
	s_mov_b32 m0, s59
	s_nop 0
	global_load_lds_dwordx4 v[244:245], off
	ds_read_b128 v[192:195], v211 offset:16384
	ds_read_b128 v[196:199], v211 offset:17408
	ds_read_b128 v[212:215], v211 offset:18432
	ds_read_b128 v[216:219], v211 offset:19456
	ds_read_b128 v[220:223], v211 offset:20480
	ds_read_b128 v[224:227], v211 offset:21504
	ds_read_b128 v[228:231], v211 offset:22528
	ds_read_b128 v[232:235], v211 offset:23552
	s_waitcnt vmcnt(8)
	s_waitcnt lgkmcnt(0)
	s_barrier
; #define PG8_STAGE(bufoff, gbase, voff) do { _Pragma("unroll") for (int _i = 0; _i < 2; ++_i) \
;         __builtin_amdgcn_global_load_lds((const unsigned*)((const char*)(gbase) + (voff)[_i]), (PG8_LAS unsigned*)(lds + (bufoff) + ldsw + _i * 8192), 16, 0, 0); } while (0)
; #define PG8_LDA(dst, b, h) do { _Pragma("unroll") for (int m = 0; m < 4; ++m) _Pragma("unroll") for (int k = 0; k < 2; ++k) dst[m][k] = *(const PG8_LAS bf16x8*)(lds + PG8_SA(b, h) + aoff + m * 2048 + k * 1024); } while (0)
; #define PG8_LDB(dst, b, h) do { _Pragma("unroll") for (int n = 0; n < 2; ++n) _Pragma("unroll") for (int k = 0; k < 2; ++k) dst[n][k] = *(const PG8_LAS bf16x8*)(lds + PG8_SB(b, h) + boff + n * 2048 + k * 1024); } while (0)
; #define PG8_MMA(ai, bj, At, Bt) do { __builtin_amdgcn_s_setprio(1); _Pragma("unroll") for (int m = 0; m < 4; ++m) _Pragma("unroll") for (int n = 0; n < 2; ++n) _Pragma("unroll") for (int k = 0; k < 2; ++k) \
;         acc[ai][bj][m][n] = __builtin_amdgcn_mfma_f32_16x16x32_bf16(Bt[n][k], At[m][k], acc[ai][bj][m][n], 0, 0, 0); __builtin_amdgcn_s_setprio(0); } while (0)
; #define PG8_WAIT_V(n) asm volatile("s_waitcnt vmcnt(" #n ")" ::: "memory")
; #define PG8_WAIT_L(n) asm volatile("s_waitcnt lgkmcnt(" #n ")" ::: "memory")
; #define PG8_BAR __builtin_amdgcn_s_barrier()
; #define PG8_SCHED __builtin_amdgcn_sched_barrier(0)
; template <class Epi, class Sched, bool ALIGN_EPI = false, bool SP2 = false>
; __device__ __forceinline__ void gemm_phase(PG8_LAS unsigned char* lds, const Gemm g, const Sched& S, const Epi& E) {
;     ...
;             PG8_WAIT_V(8); PG8_WAIT_L(0); PG8_BAR; PG8_MMA(1, 0, At, B0); PG8_MMA(1, 1, At, B1); PG8_BAR; PG8_SCHED;
;             PG8_LDB(B0, 1, 0); PG8_LDB(B1, 1, 1); PG8_SCHED; PG8_LDA(At, 1, 0); PG8_STAGE(PG8_SA(0, 1), a2 + hstep, voffA);
;             PG8_WAIT_V(8); PG8_WAIT_L(0); PG8_BAR; PG8_MMA(0, 0, At, B0); PG8_MMA(0, 1, At, B1); PG8_BAR; PG8_SCHED;
	s_setprio 1
	s_waitcnt lgkmcnt(0)
	v_mfma_f32_16x16x32_bf16 v[60:63], v[134:137], v[192:195], v[60:63]
	v_mfma_f32_16x16x32_bf16 v[56:59], v[142:145], v[192:195], v[56:59]
	v_mfma_f32_16x16x32_bf16 v[44:47], v[134:137], v[212:215], v[44:47]
	v_mfma_f32_16x16x32_bf16 v[40:43], v[142:145], v[212:215], v[40:43]
	v_mfma_f32_16x16x32_bf16 v[28:31], v[134:137], v[220:223], v[28:31]
	v_mfma_f32_16x16x32_bf16 v[24:27], v[142:145], v[220:223], v[24:27]
	v_mfma_f32_16x16x32_bf16 v[12:15], v[134:137], v[228:231], v[12:15]
	v_mfma_f32_16x16x32_bf16 v[8:11], v[142:145], v[228:231], v[8:11]
	v_mfma_f32_16x16x32_bf16 v[60:63], v[138:141], v[196:199], v[60:63]
	v_mfma_f32_16x16x32_bf16 v[56:59], v[146:149], v[196:199], v[56:59]
	v_mfma_f32_16x16x32_bf16 v[44:47], v[138:141], v[216:219], v[44:47]
	v_mfma_f32_16x16x32_bf16 v[40:43], v[146:149], v[216:219], v[40:43]
	v_mfma_f32_16x16x32_bf16 v[28:31], v[138:141], v[224:227], v[28:31]
	v_mfma_f32_16x16x32_bf16 v[24:27], v[146:149], v[224:227], v[24:27]
	v_mfma_f32_16x16x32_bf16 v[12:15], v[138:141], v[232:235], v[12:15]
	v_mfma_f32_16x16x32_bf16 v[8:11], v[146:149], v[232:235], v[8:11]
	s_setprio 0
	s_setprio 1
	v_mfma_f32_16x16x32_bf16 v[52:55], v[150:153], v[192:195], v[52:55]
	v_mfma_f32_16x16x32_bf16 v[48:51], v[184:187], v[192:195], v[48:51]
	v_mfma_f32_16x16x32_bf16 v[36:39], v[150:153], v[212:215], v[36:39]
	v_mfma_f32_16x16x32_bf16 v[32:35], v[184:187], v[212:215], v[32:35]
	v_mfma_f32_16x16x32_bf16 v[20:23], v[150:153], v[220:223], v[20:23]
	v_mfma_f32_16x16x32_bf16 v[16:19], v[184:187], v[220:223], v[16:19]
	v_mfma_f32_16x16x32_bf16 v[4:7], v[150:153], v[228:231], v[4:7]
	v_mfma_f32_16x16x32_bf16 v[0:3], v[184:187], v[228:231], v[0:3]
	v_mfma_f32_16x16x32_bf16 v[52:55], v[154:157], v[196:199], v[52:55]
	v_mfma_f32_16x16x32_bf16 v[48:51], v[188:191], v[196:199], v[48:51]
	v_mfma_f32_16x16x32_bf16 v[36:39], v[154:157], v[216:219], v[36:39]
	v_mfma_f32_16x16x32_bf16 v[32:35], v[188:191], v[216:219], v[32:35]
	v_mfma_f32_16x16x32_bf16 v[20:23], v[154:157], v[224:227], v[20:23]
	v_mfma_f32_16x16x32_bf16 v[16:19], v[188:191], v[224:227], v[16:19]
	v_mfma_f32_16x16x32_bf16 v[4:7], v[154:157], v[232:235], v[4:7]
	v_mfma_f32_16x16x32_bf16 v[0:3], v[188:191], v[232:235], v[0:3]
	s_setprio 0
	s_barrier
	s_add_i32 s74, 0, 0x18000
	s_add_i32 s75, 0, 0x1c000
	v_add_u32_e32 v146, s74, v209
	v_add_u32_e32 v188, s75, v209
	ds_read_b128 v[134:137], v146
	ds_read_b128 v[138:141], v146 offset:1024
	ds_read_b128 v[142:145], v146 offset:2048
	ds_read_b128 v[146:149], v146 offset:3072
	ds_read_b128 v[150:153], v188
	ds_read_b128 v[154:157], v188 offset:1024
	ds_read_b128 v[184:187], v188 offset:2048
	ds_read_b128 v[188:191], v188 offset:3072
	s_add_u32 s56, s56, s14
	s_addc_u32 s57, s57, 0
	s_mov_b32 m0, s60
	v_lshl_add_u64 v[246:247], s[56:57], 0, v[178:179]
	ds_read_b128 v[192:195], v211 offset:32768
	ds_read_b128 v[196:199], v211 offset:33792
	ds_read_b128 v[212:215], v211 offset:34816
	ds_read_b128 v[216:219], v211 offset:35840
	ds_read_b128 v[220:223], v211 offset:36864
	ds_read_b128 v[224:227], v211 offset:37888
	ds_read_b128 v[228:231], v211 offset:38912
	ds_read_b128 v[232:235], v211 offset:39936
	global_load_lds_dwordx4 v[246:247], off
	v_lshl_add_u64 v[246:247], s[56:57], 0, v[160:161]
	s_mov_b32 m0, s61
	s_nop 0
	global_load_lds_dwordx4 v[246:247], off
	s_waitcnt vmcnt(8)
	s_waitcnt lgkmcnt(0)
	s_barrier
	s_setprio 1
	s_waitcnt lgkmcnt(0)
	v_mfma_f32_16x16x32_bf16 v[126:129], v[134:137], v[192:195], v[126:129]
	v_mfma_f32_16x16x32_bf16 v[122:125], v[142:145], v[192:195], v[122:125]
	v_mfma_f32_16x16x32_bf16 v[110:113], v[134:137], v[212:215], v[110:113]
	v_mfma_f32_16x16x32_bf16 v[106:109], v[142:145], v[212:215], v[106:109]
	v_mfma_f32_16x16x32_bf16 v[94:97], v[134:137], v[220:223], v[94:97]
	v_mfma_f32_16x16x32_bf16 v[90:93], v[142:145], v[220:223], v[90:93]
	v_mfma_f32_16x16x32_bf16 v[76:79], v[134:137], v[228:231], v[76:79]
	v_mfma_f32_16x16x32_bf16 v[72:75], v[142:145], v[228:231], v[72:75]
	v_mfma_f32_16x16x32_bf16 v[126:129], v[138:141], v[196:199], v[126:129]
	v_mfma_f32_16x16x32_bf16 v[122:125], v[146:149], v[196:199], v[122:125]
	v_mfma_f32_16x16x32_bf16 v[110:113], v[138:141], v[216:219], v[110:113]
	v_mfma_f32_16x16x32_bf16 v[106:109], v[146:149], v[216:219], v[106:109]
	v_mfma_f32_16x16x32_bf16 v[94:97], v[138:141], v[224:227], v[94:97]
	v_mfma_f32_16x16x32_bf16 v[90:93], v[146:149], v[224:227], v[90:93]
	v_mfma_f32_16x16x32_bf16 v[76:79], v[138:141], v[232:235], v[76:79]
	v_mfma_f32_16x16x32_bf16 v[72:75], v[146:149], v[232:235], v[72:75]
	s_setprio 0
	s_setprio 1
	v_mfma_f32_16x16x32_bf16 v[118:121], v[150:153], v[192:195], v[118:121]
	v_mfma_f32_16x16x32_bf16 v[114:117], v[184:187], v[192:195], v[114:117]
	v_mfma_f32_16x16x32_bf16 v[102:105], v[150:153], v[212:215], v[102:105]
	v_mfma_f32_16x16x32_bf16 v[98:101], v[184:187], v[212:215], v[98:101]
	v_mfma_f32_16x16x32_bf16 v[86:89], v[150:153], v[220:223], v[86:89]
	v_mfma_f32_16x16x32_bf16 v[82:85], v[184:187], v[220:223], v[82:85]
	v_mfma_f32_16x16x32_bf16 v[68:71], v[150:153], v[228:231], v[68:71]
	v_mfma_f32_16x16x32_bf16 v[64:67], v[184:187], v[228:231], v[64:67]
	v_mfma_f32_16x16x32_bf16 v[118:121], v[154:157], v[196:199], v[118:121]
	v_mfma_f32_16x16x32_bf16 v[114:117], v[188:191], v[196:199], v[114:117]
	v_mfma_f32_16x16x32_bf16 v[102:105], v[154:157], v[216:219], v[102:105]
	v_mfma_f32_16x16x32_bf16 v[98:101], v[188:191], v[216:219], v[98:101]
	v_mfma_f32_16x16x32_bf16 v[86:89], v[154:157], v[224:227], v[86:89]
	v_mfma_f32_16x16x32_bf16 v[82:85], v[188:191], v[224:227], v[82:85]
	v_mfma_f32_16x16x32_bf16 v[68:71], v[154:157], v[232:235], v[68:71]
	v_mfma_f32_16x16x32_bf16 v[64:67], v[188:191], v[232:235], v[64:67]
	s_setprio 0
	s_barrier
; #define PG8_STAGE(bufoff, gbase, voff) do { _Pragma("unroll") for (int _i = 0; _i < 2; ++_i) \
;         __builtin_amdgcn_global_load_lds((const unsigned*)((const char*)(gbase) + (voff)[_i]), (PG8_LAS unsigned*)(lds + (bufoff) + ldsw + _i * 8192), 16, 0, 0); } while (0)
; #define PG8_LDA(dst, b, h) do { _Pragma("unroll") for (int m = 0; m < 4; ++m) _Pragma("unroll") for (int k = 0; k < 2; ++k) dst[m][k] = *(const PG8_LAS bf16x8*)(lds + PG8_SA(b, h) + aoff + m * 2048 + k * 1024); } while (0)
; #define PG8_MMA(ai, bj, At, Bt) do { __builtin_amdgcn_s_setprio(1); _Pragma("unroll") for (int m = 0; m < 4; ++m) _Pragma("unroll") for (int n = 0; n < 2; ++n) _Pragma("unroll") for (int k = 0; k < 2; ++k) \
;         acc[ai][bj][m][n] = __builtin_amdgcn_mfma_f32_16x16x32_bf16(Bt[n][k], At[m][k], acc[ai][bj][m][n], 0, 0, 0); __builtin_amdgcn_s_setprio(0); } while (0)
; #define PG8_WAIT_V(n) asm volatile("s_waitcnt vmcnt(" #n ")" ::: "memory")
; #define PG8_WAIT_L(n) asm volatile("s_waitcnt lgkmcnt(" #n ")" ::: "memory")
; #define PG8_BAR __builtin_amdgcn_s_barrier()
; #define PG8_SCHED __builtin_amdgcn_sched_barrier(0)
; template <class Epi, class Sched, bool ALIGN_EPI = false, bool SP2 = false>
; __device__ __forceinline__ void gemm_phase(PG8_LAS unsigned char* lds, const Gemm g, const Sched& S, const Epi& E) {
;     ...
;         for (int t = 0; t < nt; t += 2) {
;     ...
;             PG8_LDA(At, 1, 1); PG8_STAGE(PG8_SB(1, 0), b3, voffB); PG8_STAGE(PG8_SB(1, 1), b3 + hstep, voffB); PG8_STAGE(PG8_SA(1, 0), a3, voffA);
;             PG8_WAIT_V(8); PG8_WAIT_L(0); PG8_BAR; PG8_MMA(1, 0, At, B0); PG8_MMA(1, 1, At, B1); PG8_BAR; PG8_SCHED;
	s_add_i32 s56, s74, s39
	v_lshl_add_u64 v[200:201], v[200:201], 0, s[40:41]
	s_mov_b32 m0, s56
	s_nop 0
	global_load_lds_dwordx4 v[200:201], off
	v_lshl_add_u64 v[200:201], v[236:237], 0, s[40:41]
	s_add_i32 m0, s56, 0x2000
	s_add_i32 s56, s75, s39
	global_load_lds_dwordx4 v[200:201], off
	v_lshl_add_u64 v[200:201], v[238:239], 0, s[40:41]
	s_mov_b32 m0, s56
	s_nop 0
	global_load_lds_dwordx4 v[200:201], off
	v_lshl_add_u64 v[200:201], v[240:241], 0, s[40:41]
	s_add_i32 m0, s56, 0x2000
	s_nop 0
	global_load_lds_dwordx4 v[200:201], off
	v_lshl_add_u64 v[200:201], v[242:243], 0, s[40:41]
	s_mov_b32 m0, s66
	s_nop 0
	global_load_lds_dwordx4 v[200:201], off
	v_lshl_add_u64 v[200:201], v[244:245], 0, s[40:41]
	s_mov_b32 m0, s67
	s_nop 0
	global_load_lds_dwordx4 v[200:201], off
	ds_read_b128 v[192:195], v211 offset:49152
	ds_read_b128 v[196:199], v211 offset:50176
	ds_read_b128 v[212:215], v211 offset:51200
	ds_read_b128 v[216:219], v211 offset:52224
	ds_read_b128 v[220:223], v211 offset:53248
	ds_read_b128 v[224:227], v211 offset:54272
	ds_read_b128 v[228:231], v211 offset:55296
	ds_read_b128 v[232:235], v211 offset:56320
	s_waitcnt vmcnt(8)
	s_waitcnt lgkmcnt(0)
	s_barrier
	s_setprio 1
	s_waitcnt lgkmcnt(0)
	v_mfma_f32_16x16x32_bf16 v[60:63], v[134:137], v[192:195], v[60:63]
	v_mfma_f32_16x16x32_bf16 v[56:59], v[142:145], v[192:195], v[56:59]
	v_mfma_f32_16x16x32_bf16 v[44:47], v[134:137], v[212:215], v[44:47]
	v_mfma_f32_16x16x32_bf16 v[40:43], v[142:145], v[212:215], v[40:43]
	v_mfma_f32_16x16x32_bf16 v[28:31], v[134:137], v[220:223], v[28:31]
	v_mfma_f32_16x16x32_bf16 v[24:27], v[142:145], v[220:223], v[24:27]
	v_mfma_f32_16x16x32_bf16 v[12:15], v[134:137], v[228:231], v[12:15]
	v_mfma_f32_16x16x32_bf16 v[8:11], v[142:145], v[228:231], v[8:11]
	v_mfma_f32_16x16x32_bf16 v[60:63], v[138:141], v[196:199], v[60:63]
	v_mfma_f32_16x16x32_bf16 v[56:59], v[146:149], v[196:199], v[56:59]
	v_mfma_f32_16x16x32_bf16 v[44:47], v[138:141], v[216:219], v[44:47]
	v_mfma_f32_16x16x32_bf16 v[40:43], v[146:149], v[216:219], v[40:43]
	v_mfma_f32_16x16x32_bf16 v[28:31], v[138:141], v[224:227], v[28:31]
	v_mfma_f32_16x16x32_bf16 v[24:27], v[146:149], v[224:227], v[24:27]
	v_mfma_f32_16x16x32_bf16 v[12:15], v[138:141], v[232:235], v[12:15]
	v_mfma_f32_16x16x32_bf16 v[8:11], v[146:149], v[232:235], v[8:11]
	s_setprio 0
	s_setprio 1
	v_mfma_f32_16x16x32_bf16 v[52:55], v[150:153], v[192:195], v[52:55]
	v_mfma_f32_16x16x32_bf16 v[48:51], v[184:187], v[192:195], v[48:51]
	v_mfma_f32_16x16x32_bf16 v[36:39], v[150:153], v[212:215], v[36:39]
	v_mfma_f32_16x16x32_bf16 v[32:35], v[184:187], v[212:215], v[32:35]
	v_mfma_f32_16x16x32_bf16 v[20:23], v[150:153], v[220:223], v[20:23]
	v_mfma_f32_16x16x32_bf16 v[16:19], v[184:187], v[220:223], v[16:19]
	v_mfma_f32_16x16x32_bf16 v[4:7], v[150:153], v[228:231], v[4:7]
	v_mfma_f32_16x16x32_bf16 v[0:3], v[184:187], v[228:231], v[0:3]
	v_mfma_f32_16x16x32_bf16 v[52:55], v[154:157], v[196:199], v[52:55]
	v_mfma_f32_16x16x32_bf16 v[48:51], v[188:191], v[196:199], v[48:51]
	v_mfma_f32_16x16x32_bf16 v[36:39], v[154:157], v[216:219], v[36:39]
	v_mfma_f32_16x16x32_bf16 v[32:35], v[188:191], v[216:219], v[32:35]
	v_mfma_f32_16x16x32_bf16 v[20:23], v[154:157], v[224:227], v[20:23]
	v_mfma_f32_16x16x32_bf16 v[16:19], v[188:191], v[224:227], v[16:19]
	v_mfma_f32_16x16x32_bf16 v[4:7], v[154:157], v[232:235], v[4:7]
	v_mfma_f32_16x16x32_bf16 v[0:3], v[188:191], v[232:235], v[0:3]
	s_setprio 0
	s_barrier
	s_add_u32 s54, s54, 0x100
	s_addc_u32 s55, s55, 0
	s_cmp_ge_u32 s73, s63
	s_mov_b32 s56, s73
	s_cbranch_scc1 .LBB0_386
